# v5 + sc1 write-through on P7/P8/P12 epilogue stores, P4 rs loads hoisted
# baseline (speedup 1.0000x reference)
; __device__ __forceinline__ unsigned cvt_pk_bf16(float lo, float hi) { unsigned r; asm volatile("v_cvt_pk_bf16_f32 %0, %1, %2" : "=v"(r) : "v"(lo), "v"(hi)); return r; }
;     __device__ __forceinline__ void operator()(const f32x4 (&acc)[2][2][4][2], const Unit& u, int wr, int wc, int fr, int fq) const {
;         const int row0 = u.pm * BM + wr * 64 + fr, col0 = u.pn * BM + wc * 32 + 8 * fq;
; #pragma unroll
;         for (int ai = 0; ai < 2; ++ai)
; #pragma unroll
;             for (int m = 0; m < 4; ++m) { bf16_t* rowp = O + (size_t)(row0 + ai * HALF + m * 16) * ldc + col0; const float r = rs[row0 + ai * HALF + m * 16];
; #pragma unroll
;                 for (int bj = 0; bj < 2; ++bj) { const f32x4 v0 = acc[ai][bj][m][0] * r, v1 = acc[ai][bj][m][1] * r;
;                     u32x4 w; w.x = cvt_pk_bf16(v0[0], v0[1]); w.y = cvt_pk_bf16(v0[2], v0[3]); w.z = cvt_pk_bf16(v1[0], v1[1]); w.w = cvt_pk_bf16(v1[2], v1[3]);
;                     *(u32x4*)(rowp + bj * HALF) = w; } }
;     }
.LBB0_523:
	v_lshl_or_b32 v144, s95, 8, v149
	v_lshl_add_u32 v140, s96, 8, v148
	v_ashrrev_i32_e32 v145, 31, v144
	v_mov_b64_e32 v[142:143], s[4:5]
	v_ashrrev_i32_e32 v141, 31, v140
	v_mad_i64_i32 v[146:147], s[0:1], v140, s76, v[142:143]
	v_lshlrev_b64 v[144:145], 1, v[144:145]
	v_lshl_add_u64 v[156:157], v[146:147], 0, v[144:145]
	v_lshl_add_u64 v[146:147], v[140:141], 2, s[36:37]
	global_load_dword v190, v[146:147], off
	global_load_dword v192, v[146:147], off offset:64
	global_load_dword v194, v[146:147], off offset:128
	global_load_dword v196, v[146:147], off offset:192
	global_load_dword v198, v[146:147], off offset:512
	global_load_dword v200, v[146:147], off offset:576
	global_load_dword v202, v[146:147], off offset:640
	global_load_dword v204, v[146:147], off offset:704
	s_mov_b64 s[14:15], -1
	s_cmp_eq_u32 s70, s71
	s_waitcnt vmcnt(7)
	v_pk_mul_f32 v[126:127], v[126:127], v[190:191] op_sel_hi:[1,0]
	v_pk_mul_f32 v[124:125], v[124:125], v[190:191] op_sel_hi:[1,0]
	v_pk_mul_f32 v[160:161], v[122:123], v[190:191] op_sel_hi:[1,0]
	v_pk_mul_f32 v[122:123], v[120:121], v[190:191] op_sel_hi:[1,0]
	v_cvt_pk_bf16_f32 v120, v124, v125
	v_cvt_pk_bf16_f32 v121, v126, v127
	v_pk_mul_f32 v[116:117], v[116:117], v[190:191] op_sel_hi:[1,0]
	v_cvt_pk_bf16_f32 v122, v122, v123
	v_cvt_pk_bf16_f32 v123, v160, v161
	global_store_dwordx4 v[156:157], v[120:123], off
	v_pk_mul_f32 v[118:119], v[118:119], v[190:191] op_sel_hi:[1,0]
	s_nop 0
	v_pk_mul_f32 v[120:121], v[114:115], v[190:191] op_sel_hi:[1,0]
	v_pk_mul_f32 v[114:115], v[112:113], v[190:191] op_sel_hi:[1,0]
	v_cvt_pk_bf16_f32 v112, v116, v117
	v_cvt_pk_bf16_f32 v113, v118, v119
	s_nop 0
	v_cvt_pk_bf16_f32 v114, v114, v115
	v_cvt_pk_bf16_f32 v115, v120, v121
	global_store_dwordx4 v[156:157], v[112:115], off offset:256
	s_nop 1
	v_or_b32_e32 v112, 16, v140
	v_ashrrev_i32_e32 v113, 31, v112
	v_mad_i64_i32 v[114:115], s[0:1], v112, s76, v[142:143]
	v_lshl_add_u64 v[112:113], v[112:113], 2, s[36:37]
	s_nop 0
	v_lshl_add_u64 v[114:115], v[114:115], 0, v[144:145]
	s_waitcnt vmcnt(8)
	v_pk_mul_f32 v[110:111], v[110:111], v[192:193] op_sel_hi:[1,0]
	v_pk_mul_f32 v[108:109], v[108:109], v[192:193] op_sel_hi:[1,0]
	v_pk_mul_f32 v[116:117], v[106:107], v[192:193] op_sel_hi:[1,0]
	v_pk_mul_f32 v[106:107], v[104:105], v[192:193] op_sel_hi:[1,0]
	v_cvt_pk_bf16_f32 v104, v108, v109
	v_cvt_pk_bf16_f32 v105, v110, v111
	v_pk_mul_f32 v[100:101], v[100:101], v[192:193] op_sel_hi:[1,0]
	v_cvt_pk_bf16_f32 v106, v106, v107
	v_cvt_pk_bf16_f32 v107, v116, v117
	global_store_dwordx4 v[114:115], v[104:107], off
	v_pk_mul_f32 v[102:103], v[102:103], v[192:193] op_sel_hi:[1,0]
	s_nop 0
	v_pk_mul_f32 v[104:105], v[98:99], v[192:193] op_sel_hi:[1,0]
	v_pk_mul_f32 v[98:99], v[96:97], v[192:193] op_sel_hi:[1,0]
	v_cvt_pk_bf16_f32 v96, v100, v101
	v_cvt_pk_bf16_f32 v97, v102, v103
	s_nop 0
	v_cvt_pk_bf16_f32 v98, v98, v99
	v_cvt_pk_bf16_f32 v99, v104, v105
	global_store_dwordx4 v[114:115], v[96:99], off offset:256
	s_nop 1
	v_or_b32_e32 v96, 32, v140
	v_ashrrev_i32_e32 v97, 31, v96
	v_mad_i64_i32 v[98:99], s[0:1], v96, s76, v[142:143]
	v_lshl_add_u64 v[96:97], v[96:97], 2, s[36:37]
	s_nop 0
	v_lshl_add_u64 v[98:99], v[98:99], 0, v[144:145]
	s_waitcnt vmcnt(9)
	v_pk_mul_f32 v[94:95], v[94:95], v[194:195] op_sel_hi:[1,0]
	v_pk_mul_f32 v[92:93], v[92:93], v[194:195] op_sel_hi:[1,0]
	v_pk_mul_f32 v[100:101], v[90:91], v[194:195] op_sel_hi:[1,0]
	v_pk_mul_f32 v[90:91], v[88:89], v[194:195] op_sel_hi:[1,0]
	v_cvt_pk_bf16_f32 v88, v92, v93
	v_cvt_pk_bf16_f32 v89, v94, v95
	v_pk_mul_f32 v[84:85], v[84:85], v[194:195] op_sel_hi:[1,0]
	v_cvt_pk_bf16_f32 v90, v90, v91
	v_cvt_pk_bf16_f32 v91, v100, v101
	global_store_dwordx4 v[98:99], v[88:91], off
	v_pk_mul_f32 v[86:87], v[86:87], v[194:195] op_sel_hi:[1,0]
	s_nop 0
	v_pk_mul_f32 v[88:89], v[82:83], v[194:195] op_sel_hi:[1,0]
	v_pk_mul_f32 v[82:83], v[80:81], v[194:195] op_sel_hi:[1,0]
	v_cvt_pk_bf16_f32 v80, v84, v85
	v_cvt_pk_bf16_f32 v81, v86, v87
	s_nop 0
	v_cvt_pk_bf16_f32 v82, v82, v83
	v_cvt_pk_bf16_f32 v83, v88, v89
	global_store_dwordx4 v[98:99], v[80:83], off offset:256
	s_nop 1
	v_or_b32_e32 v80, 48, v140
	v_ashrrev_i32_e32 v81, 31, v80
	v_mad_i64_i32 v[82:83], s[0:1], v80, s76, v[142:143]
	v_lshl_add_u64 v[80:81], v[80:81], 2, s[36:37]
	s_nop 0
	v_lshl_add_u64 v[82:83], v[82:83], 0, v[144:145]
	s_waitcnt vmcnt(10)
; __device__ __forceinline__ unsigned cvt_pk_bf16(float lo, float hi) { unsigned r; asm volatile("v_cvt_pk_bf16_f32 %0, %1, %2" : "=v"(r) : "v"(lo), "v"(hi)); return r; }
;     __device__ __forceinline__ void operator()(const f32x4 (&acc)[2][2][4][2], const Unit& u, int wr, int wc, int fr, int fq) const {
;     ...
; #pragma unroll
;         for (int ai = 0; ai < 2; ++ai)
; #pragma unroll
;             for (int m = 0; m < 4; ++m) { bf16_t* rowp = O + (size_t)(row0 + ai * HALF + m * 16) * ldc + col0; const float r = rs[row0 + ai * HALF + m * 16];
; #pragma unroll
;                 for (int bj = 0; bj < 2; ++bj) { const f32x4 v0 = acc[ai][bj][m][0] * r, v1 = acc[ai][bj][m][1] * r;
;                     u32x4 w; w.x = cvt_pk_bf16(v0[0], v0[1]); w.y = cvt_pk_bf16(v0[2], v0[3]); w.z = cvt_pk_bf16(v1[0], v1[1]); w.w = cvt_pk_bf16(v1[2], v1[3]);
;                     *(u32x4*)(rowp + bj * HALF) = w; } }
;     }
	v_pk_mul_f32 v[78:79], v[78:79], v[196:197] op_sel_hi:[1,0]
	v_pk_mul_f32 v[76:77], v[76:77], v[196:197] op_sel_hi:[1,0]
	v_pk_mul_f32 v[84:85], v[74:75], v[196:197] op_sel_hi:[1,0]
	v_pk_mul_f32 v[74:75], v[72:73], v[196:197] op_sel_hi:[1,0]
	v_cvt_pk_bf16_f32 v72, v76, v77
	v_cvt_pk_bf16_f32 v73, v78, v79
	v_pk_mul_f32 v[70:71], v[70:71], v[196:197] op_sel_hi:[1,0]
	v_cvt_pk_bf16_f32 v74, v74, v75
	v_cvt_pk_bf16_f32 v75, v84, v85
	global_store_dwordx4 v[82:83], v[72:75], off
	v_pk_mul_f32 v[68:69], v[68:69], v[196:197] op_sel_hi:[1,0]
	s_nop 0
	v_pk_mul_f32 v[72:73], v[66:67], v[196:197] op_sel_hi:[1,0]
	v_pk_mul_f32 v[66:67], v[64:65], v[196:197] op_sel_hi:[1,0]
	v_cvt_pk_bf16_f32 v64, v68, v69
	v_cvt_pk_bf16_f32 v65, v70, v71
	s_nop 0
	v_cvt_pk_bf16_f32 v66, v66, v67
	v_cvt_pk_bf16_f32 v67, v72, v73
	global_store_dwordx4 v[82:83], v[64:67], off offset:256
	s_nop 0
	s_waitcnt vmcnt(11)
	v_pk_mul_f32 v[62:63], v[62:63], v[198:199] op_sel_hi:[1,0]
	v_add_u32_e32 v64, 0x80, v140
	v_mad_i64_i32 v[64:65], s[0:1], v64, s76, v[142:143]
	v_lshl_add_u64 v[64:65], v[64:65], 0, v[144:145]
	v_pk_mul_f32 v[60:61], v[60:61], v[198:199] op_sel_hi:[1,0]
	v_pk_mul_f32 v[68:69], v[58:59], v[198:199] op_sel_hi:[1,0]
	v_pk_mul_f32 v[58:59], v[56:57], v[198:199] op_sel_hi:[1,0]
	v_cvt_pk_bf16_f32 v56, v60, v61
	v_cvt_pk_bf16_f32 v57, v62, v63
	v_pk_mul_f32 v[54:55], v[54:55], v[198:199] op_sel_hi:[1,0]
	v_cvt_pk_bf16_f32 v58, v58, v59
	v_cvt_pk_bf16_f32 v59, v68, v69
	global_store_dwordx4 v[64:65], v[56:59], off
	v_pk_mul_f32 v[52:53], v[52:53], v[198:199] op_sel_hi:[1,0]
	s_nop 0
	v_pk_mul_f32 v[56:57], v[50:51], v[198:199] op_sel_hi:[1,0]
	v_pk_mul_f32 v[50:51], v[48:49], v[198:199] op_sel_hi:[1,0]
	v_cvt_pk_bf16_f32 v48, v52, v53
	v_cvt_pk_bf16_f32 v49, v54, v55
	s_nop 0
	v_cvt_pk_bf16_f32 v50, v50, v51
	v_cvt_pk_bf16_f32 v51, v56, v57
	global_store_dwordx4 v[64:65], v[48:51], off offset:256
	s_nop 0
	s_waitcnt vmcnt(12)
	v_pk_mul_f32 v[46:47], v[46:47], v[200:201] op_sel_hi:[1,0]
	v_add_u32_e32 v48, 0x90, v140
	v_mad_i64_i32 v[48:49], s[0:1], v48, s76, v[142:143]
	v_lshl_add_u64 v[48:49], v[48:49], 0, v[144:145]
	v_pk_mul_f32 v[44:45], v[44:45], v[200:201] op_sel_hi:[1,0]
	v_pk_mul_f32 v[52:53], v[42:43], v[200:201] op_sel_hi:[1,0]
	v_pk_mul_f32 v[42:43], v[40:41], v[200:201] op_sel_hi:[1,0]
	v_cvt_pk_bf16_f32 v40, v44, v45
	v_cvt_pk_bf16_f32 v41, v46, v47
	v_pk_mul_f32 v[38:39], v[38:39], v[200:201] op_sel_hi:[1,0]
	v_cvt_pk_bf16_f32 v42, v42, v43
	v_cvt_pk_bf16_f32 v43, v52, v53
	global_store_dwordx4 v[48:49], v[40:43], off
	v_pk_mul_f32 v[36:37], v[36:37], v[200:201] op_sel_hi:[1,0]
	s_nop 0
	v_pk_mul_f32 v[40:41], v[34:35], v[200:201] op_sel_hi:[1,0]
	v_pk_mul_f32 v[34:35], v[32:33], v[200:201] op_sel_hi:[1,0]
	v_cvt_pk_bf16_f32 v32, v36, v37
	v_cvt_pk_bf16_f32 v33, v38, v39
	s_nop 0
	v_cvt_pk_bf16_f32 v34, v34, v35
	v_cvt_pk_bf16_f32 v35, v40, v41
	global_store_dwordx4 v[48:49], v[32:35], off offset:256
	s_nop 0
	s_waitcnt vmcnt(13)
	v_pk_mul_f32 v[30:31], v[30:31], v[202:203] op_sel_hi:[1,0]
	v_add_u32_e32 v32, 0xa0, v140
	v_mad_i64_i32 v[32:33], s[0:1], v32, s76, v[142:143]
	v_lshl_add_u64 v[32:33], v[32:33], 0, v[144:145]
	v_pk_mul_f32 v[28:29], v[28:29], v[202:203] op_sel_hi:[1,0]
	v_pk_mul_f32 v[36:37], v[26:27], v[202:203] op_sel_hi:[1,0]
	v_pk_mul_f32 v[26:27], v[24:25], v[202:203] op_sel_hi:[1,0]
	v_cvt_pk_bf16_f32 v24, v28, v29
	v_cvt_pk_bf16_f32 v25, v30, v31
	v_pk_mul_f32 v[22:23], v[22:23], v[202:203] op_sel_hi:[1,0]
	v_cvt_pk_bf16_f32 v26, v26, v27
	v_cvt_pk_bf16_f32 v27, v36, v37
	global_store_dwordx4 v[32:33], v[24:27], off
	v_pk_mul_f32 v[20:21], v[20:21], v[202:203] op_sel_hi:[1,0]
	s_nop 0
	v_pk_mul_f32 v[24:25], v[18:19], v[202:203] op_sel_hi:[1,0]
	v_pk_mul_f32 v[18:19], v[16:17], v[202:203] op_sel_hi:[1,0]
	v_cvt_pk_bf16_f32 v16, v20, v21
	v_cvt_pk_bf16_f32 v17, v22, v23
	s_nop 0
	v_cvt_pk_bf16_f32 v18, v18, v19
	v_cvt_pk_bf16_f32 v19, v24, v25
	global_store_dwordx4 v[32:33], v[16:19], off offset:256
	s_nop 0
	s_waitcnt vmcnt(14)
	v_pk_mul_f32 v[14:15], v[14:15], v[204:205] op_sel_hi:[1,0]
	v_add_u32_e32 v16, 0xb0, v140
	v_mad_i64_i32 v[16:17], s[0:1], v16, s76, v[142:143]
	v_lshl_add_u64 v[16:17], v[16:17], 0, v[144:145]
	v_pk_mul_f32 v[12:13], v[12:13], v[204:205] op_sel_hi:[1,0]
	v_pk_mul_f32 v[20:21], v[10:11], v[204:205] op_sel_hi:[1,0]
	v_pk_mul_f32 v[10:11], v[8:9], v[204:205] op_sel_hi:[1,0]
	v_cvt_pk_bf16_f32 v8, v12, v13
	v_cvt_pk_bf16_f32 v9, v14, v15
	v_pk_mul_f32 v[6:7], v[6:7], v[204:205] op_sel_hi:[1,0]
	v_cvt_pk_bf16_f32 v10, v10, v11
	v_cvt_pk_bf16_f32 v11, v20, v21
	global_store_dwordx4 v[16:17], v[8:11], off
	v_pk_mul_f32 v[4:5], v[4:5], v[204:205] op_sel_hi:[1,0]
	s_nop 0
	v_pk_mul_f32 v[8:9], v[2:3], v[204:205] op_sel_hi:[1,0]
	v_pk_mul_f32 v[2:3], v[0:1], v[204:205] op_sel_hi:[1,0]
	v_cvt_pk_bf16_f32 v0, v4, v5
	v_cvt_pk_bf16_f32 v1, v6, v7
	s_nop 0
	v_cvt_pk_bf16_f32 v2, v2, v3
	v_cvt_pk_bf16_f32 v3, v8, v9
	global_store_dwordx4 v[16:17], v[0:3], off offset:256
	s_cbranch_scc1 .LBB0_512
	s_andn2_b64 vcc, exec, s[6:7]
	s_cbranch_vccnz .LBB0_511
	s_barrier
	s_branch .LBB0_511

; __device__ __forceinline__ unsigned cvt_pk_bf16(float lo, float hi) { unsigned r; asm volatile("v_cvt_pk_bf16_f32 %0, %1, %2" : "=v"(r) : "v"(lo), "v"(hi)); return r; }
;     __device__ __forceinline__ void operator()(const f32x4 (&acc)[2][2][4][2], const Unit& u, int wr, int wc, int fr, int fq) const {
;         const int row0 = u.pm * BM + wr * 64 + fr, col0 = u.pn * 128 + wc * 32 + 8 * fq;
; #pragma unroll
;         for (int ai = 0; ai < 2; ++ai)
; #pragma unroll
;             for (int m = 0; m < 4; ++m) { const size_t off = (size_t)(row0 + ai * HALF + m * 16) * 1024 + col0; const float r = rs[row0 + ai * HALF + m * 16];
; #pragma unroll
;                 for (int bj = 0; bj < 2; ++bj) { const f32x4 v0 = acc[ai][bj][m][0] * r, v1 = acc[ai][bj][m][1] * r;
;                     u32x4 w; w.x = cvt_pk_bf16(v0[0], v0[1]); w.y = cvt_pk_bf16(v0[2], v0[3]); w.z = cvt_pk_bf16(v1[0], v1[1]); w.w = cvt_pk_bf16(v1[2], v1[3]);
;                     *(u32x4*)((bj ? va : ka) + off) = w; } }
;     }
.LBB0_538:
	v_lshl_add_u32 v152, s71, 8, v146
	v_ashrrev_i32_e32 v153, 31, v152
	v_lshl_add_u64 v[140:141], v[152:153], 2, s[10:11]
	global_load_dword v190, v[140:141], off
	global_load_dword v192, v[140:141], off offset:64
	global_load_dword v194, v[140:141], off offset:128
	global_load_dword v196, v[140:141], off offset:192
	global_load_dword v198, v[140:141], off offset:512
	global_load_dword v200, v[140:141], off offset:576
	global_load_dword v202, v[140:141], off offset:640
	global_load_dword v204, v[140:141], off offset:704
	v_lshl_or_b32 v142, s6, 7, v148
	v_ashrrev_i32_e32 v143, 31, v142
	v_lshlrev_b64 v[144:145], 11, v[152:153]
	v_or_b32_e32 v156, 16, v152
	v_lshlrev_b64 v[142:143], 1, v[142:143]
	v_lshl_add_u64 v[158:159], s[54:55], 0, v[144:145]
	v_lshl_add_u64 v[160:161], s[2:3], 0, v[144:145]
	v_ashrrev_i32_e32 v157, 31, v156
	v_lshl_add_u64 v[158:159], v[158:159], 0, v[142:143]
	v_lshl_add_u64 v[160:161], v[160:161], 0, v[142:143]
	v_lshl_add_u64 v[162:163], v[156:157], 2, s[10:11]
	s_mov_b64 s[0:1], 0x40000
	s_cmp_eq_u32 s7, 2
	s_waitcnt vmcnt(7)
	v_pk_mul_f32 v[126:127], v[126:127], v[190:191] op_sel_hi:[1,0]
	v_pk_mul_f32 v[124:125], v[124:125], v[190:191] op_sel_hi:[1,0]
	v_pk_mul_f32 v[122:123], v[122:123], v[190:191] op_sel_hi:[1,0]
	v_pk_mul_f32 v[120:121], v[120:121], v[190:191] op_sel_hi:[1,0]
	v_pk_mul_f32 v[118:119], v[118:119], v[190:191] op_sel_hi:[1,0]
	v_pk_mul_f32 v[116:117], v[116:117], v[190:191] op_sel_hi:[1,0]
	v_pk_mul_f32 v[164:165], v[114:115], v[190:191] op_sel_hi:[1,0]
	v_pk_mul_f32 v[154:155], v[112:113], v[190:191] op_sel_hi:[1,0]
	v_cvt_pk_bf16_f32 v112, v124, v125
	v_cvt_pk_bf16_f32 v113, v126, v127
	v_cvt_pk_bf16_f32 v114, v120, v121
	v_cvt_pk_bf16_f32 v115, v122, v123
	global_store_dwordx4 v[158:159], v[112:115], off
	s_nop 1
	v_cvt_pk_bf16_f32 v112, v116, v117
	v_cvt_pk_bf16_f32 v113, v118, v119
	v_cvt_pk_bf16_f32 v114, v154, v155
	v_cvt_pk_bf16_f32 v115, v164, v165
	global_store_dwordx4 v[160:161], v[112:115], off
	s_nop 0
	v_lshlrev_b64 v[116:117], 11, v[156:157]
	v_or_b32_e32 v114, 32, v152
	v_lshl_add_u64 v[120:121], s[54:55], 0, v[116:117]
	v_lshl_add_u64 v[116:117], s[2:3], 0, v[116:117]
	v_ashrrev_i32_e32 v115, 31, v114
	v_lshl_add_u64 v[120:121], v[120:121], 0, v[142:143]
	v_lshl_add_u64 v[116:117], v[116:117], 0, v[142:143]
	v_lshl_add_u64 v[118:119], v[114:115], 2, s[10:11]
	s_waitcnt vmcnt(8)
	v_pk_mul_f32 v[110:111], v[110:111], v[192:193] op_sel_hi:[1,0]
	v_pk_mul_f32 v[108:109], v[108:109], v[192:193] op_sel_hi:[1,0]
	v_pk_mul_f32 v[106:107], v[106:107], v[192:193] op_sel_hi:[1,0]
	v_pk_mul_f32 v[104:105], v[104:105], v[192:193] op_sel_hi:[1,0]
	v_pk_mul_f32 v[102:103], v[102:103], v[192:193] op_sel_hi:[1,0]
	v_pk_mul_f32 v[100:101], v[100:101], v[192:193] op_sel_hi:[1,0]
	v_pk_mul_f32 v[122:123], v[98:99], v[192:193] op_sel_hi:[1,0]
	v_pk_mul_f32 v[112:113], v[96:97], v[192:193] op_sel_hi:[1,0]
	v_cvt_pk_bf16_f32 v96, v108, v109
	v_cvt_pk_bf16_f32 v97, v110, v111
	v_cvt_pk_bf16_f32 v98, v104, v105
	v_cvt_pk_bf16_f32 v99, v106, v107
	global_store_dwordx4 v[120:121], v[96:99], off
	s_nop 1
	v_cvt_pk_bf16_f32 v96, v100, v101
	v_cvt_pk_bf16_f32 v97, v102, v103
	v_cvt_pk_bf16_f32 v98, v112, v113
	v_cvt_pk_bf16_f32 v99, v122, v123
	global_store_dwordx4 v[116:117], v[96:99], off
	s_nop 0
	v_lshlrev_b64 v[100:101], 11, v[114:115]
	v_or_b32_e32 v98, 48, v152
	v_lshl_add_u64 v[104:105], s[54:55], 0, v[100:101]
	v_lshl_add_u64 v[100:101], s[2:3], 0, v[100:101]
	v_ashrrev_i32_e32 v99, 31, v98
	v_lshl_add_u64 v[104:105], v[104:105], 0, v[142:143]
	v_lshl_add_u64 v[100:101], v[100:101], 0, v[142:143]
	v_lshl_add_u64 v[102:103], v[98:99], 2, s[10:11]
	s_waitcnt vmcnt(9)
	v_pk_mul_f32 v[94:95], v[94:95], v[194:195] op_sel_hi:[1,0]
	v_pk_mul_f32 v[92:93], v[92:93], v[194:195] op_sel_hi:[1,0]
	v_pk_mul_f32 v[90:91], v[90:91], v[194:195] op_sel_hi:[1,0]
	v_pk_mul_f32 v[88:89], v[88:89], v[194:195] op_sel_hi:[1,0]
	v_pk_mul_f32 v[86:87], v[86:87], v[194:195] op_sel_hi:[1,0]
	v_pk_mul_f32 v[84:85], v[84:85], v[194:195] op_sel_hi:[1,0]
	v_pk_mul_f32 v[106:107], v[82:83], v[194:195] op_sel_hi:[1,0]
	v_pk_mul_f32 v[96:97], v[80:81], v[194:195] op_sel_hi:[1,0]
	v_cvt_pk_bf16_f32 v80, v92, v93
	v_cvt_pk_bf16_f32 v81, v94, v95
	v_cvt_pk_bf16_f32 v82, v88, v89
	v_cvt_pk_bf16_f32 v83, v90, v91
	global_store_dwordx4 v[104:105], v[80:83], off
	s_nop 1
	v_cvt_pk_bf16_f32 v80, v84, v85
	v_cvt_pk_bf16_f32 v81, v86, v87
	v_cvt_pk_bf16_f32 v82, v96, v97
	v_cvt_pk_bf16_f32 v83, v106, v107
	global_store_dwordx4 v[100:101], v[80:83], off
	s_nop 0
	s_waitcnt vmcnt(10)
	v_pk_mul_f32 v[78:79], v[78:79], v[196:197] op_sel_hi:[1,0]
	v_lshlrev_b64 v[82:83], 11, v[98:99]
	v_lshl_add_u64 v[84:85], s[54:55], 0, v[82:83]
	v_lshl_add_u64 v[82:83], s[2:3], 0, v[82:83]
	v_lshl_add_u64 v[84:85], v[84:85], 0, v[142:143]
	v_lshl_add_u64 v[82:83], v[82:83], 0, v[142:143]
	v_pk_mul_f32 v[76:77], v[76:77], v[196:197] op_sel_hi:[1,0]
	v_pk_mul_f32 v[74:75], v[74:75], v[196:197] op_sel_hi:[1,0]
	v_pk_mul_f32 v[72:73], v[72:73], v[196:197] op_sel_hi:[1,0]
	v_pk_mul_f32 v[70:71], v[70:71], v[196:197] op_sel_hi:[1,0]
	v_pk_mul_f32 v[68:69], v[68:69], v[196:197] op_sel_hi:[1,0]
	v_pk_mul_f32 v[86:87], v[66:67], v[196:197] op_sel_hi:[1,0]
	v_pk_mul_f32 v[80:81], v[64:65], v[196:197] op_sel_hi:[1,0]
	v_cvt_pk_bf16_f32 v64, v76, v77
	v_cvt_pk_bf16_f32 v65, v78, v79
	v_cvt_pk_bf16_f32 v66, v72, v73
	v_cvt_pk_bf16_f32 v67, v74, v75
	global_store_dwordx4 v[84:85], v[64:67], off
	s_nop 1
	v_cvt_pk_bf16_f32 v64, v68, v69
	v_cvt_pk_bf16_f32 v65, v70, v71
	v_cvt_pk_bf16_f32 v66, v80, v81
	v_cvt_pk_bf16_f32 v67, v86, v87
	global_store_dwordx4 v[82:83], v[64:67], off
	s_nop 0
	s_waitcnt vmcnt(11)
; __device__ __forceinline__ unsigned cvt_pk_bf16(float lo, float hi) { unsigned r; asm volatile("v_cvt_pk_bf16_f32 %0, %1, %2" : "=v"(r) : "v"(lo), "v"(hi)); return r; }
;     __device__ __forceinline__ void operator()(const f32x4 (&acc)[2][2][4][2], const Unit& u, int wr, int wc, int fr, int fq) const {
;     ...
;         for (int ai = 0; ai < 2; ++ai)
; #pragma unroll
;             for (int m = 0; m < 4; ++m) { const size_t off = (size_t)(row0 + ai * HALF + m * 16) * 1024 + col0; const float r = rs[row0 + ai * HALF + m * 16];
; #pragma unroll
;                 for (int bj = 0; bj < 2; ++bj) { const f32x4 v0 = acc[ai][bj][m][0] * r, v1 = acc[ai][bj][m][1] * r;
;                     u32x4 w; w.x = cvt_pk_bf16(v0[0], v0[1]); w.y = cvt_pk_bf16(v0[2], v0[3]); w.z = cvt_pk_bf16(v1[0], v1[1]); w.w = cvt_pk_bf16(v1[2], v1[3]);
;                     *(u32x4*)((bj ? va : ka) + off) = w; } }
;     }
	v_pk_mul_f32 v[62:63], v[62:63], v[198:199] op_sel_hi:[1,0]
	v_lshl_add_u64 v[66:67], v[144:145], 0, s[0:1]
	v_lshl_add_u64 v[68:69], s[54:55], 0, v[66:67]
	v_lshl_add_u64 v[66:67], s[2:3], 0, v[66:67]
	v_lshl_add_u64 v[68:69], v[68:69], 0, v[142:143]
	v_lshl_add_u64 v[66:67], v[66:67], 0, v[142:143]
	v_pk_mul_f32 v[60:61], v[60:61], v[198:199] op_sel_hi:[1,0]
	v_pk_mul_f32 v[58:59], v[58:59], v[198:199] op_sel_hi:[1,0]
	v_pk_mul_f32 v[56:57], v[56:57], v[198:199] op_sel_hi:[1,0]
	v_pk_mul_f32 v[54:55], v[54:55], v[198:199] op_sel_hi:[1,0]
	v_pk_mul_f32 v[52:53], v[52:53], v[198:199] op_sel_hi:[1,0]
	v_pk_mul_f32 v[70:71], v[50:51], v[198:199] op_sel_hi:[1,0]
	v_pk_mul_f32 v[64:65], v[48:49], v[198:199] op_sel_hi:[1,0]
	v_cvt_pk_bf16_f32 v48, v60, v61
	v_cvt_pk_bf16_f32 v49, v62, v63
	v_cvt_pk_bf16_f32 v50, v56, v57
	v_cvt_pk_bf16_f32 v51, v58, v59
	global_store_dwordx4 v[68:69], v[48:51], off
	s_mov_b64 s[0:1], 0x48000
	s_nop 0
	v_cvt_pk_bf16_f32 v48, v52, v53
	v_cvt_pk_bf16_f32 v49, v54, v55
	v_cvt_pk_bf16_f32 v50, v64, v65
	v_cvt_pk_bf16_f32 v51, v70, v71
	global_store_dwordx4 v[66:67], v[48:51], off
	s_nop 0
	s_waitcnt vmcnt(12)
	v_pk_mul_f32 v[46:47], v[46:47], v[200:201] op_sel_hi:[1,0]
	v_lshl_add_u64 v[50:51], v[144:145], 0, s[0:1]
	v_lshl_add_u64 v[52:53], s[54:55], 0, v[50:51]
	v_lshl_add_u64 v[50:51], s[2:3], 0, v[50:51]
	v_lshl_add_u64 v[52:53], v[52:53], 0, v[142:143]
	v_lshl_add_u64 v[50:51], v[50:51], 0, v[142:143]
	v_pk_mul_f32 v[44:45], v[44:45], v[200:201] op_sel_hi:[1,0]
	v_pk_mul_f32 v[42:43], v[42:43], v[200:201] op_sel_hi:[1,0]
	v_pk_mul_f32 v[40:41], v[40:41], v[200:201] op_sel_hi:[1,0]
	v_pk_mul_f32 v[38:39], v[38:39], v[200:201] op_sel_hi:[1,0]
	v_pk_mul_f32 v[36:37], v[36:37], v[200:201] op_sel_hi:[1,0]
	v_pk_mul_f32 v[54:55], v[34:35], v[200:201] op_sel_hi:[1,0]
	v_pk_mul_f32 v[48:49], v[32:33], v[200:201] op_sel_hi:[1,0]
	v_cvt_pk_bf16_f32 v32, v44, v45
	v_cvt_pk_bf16_f32 v33, v46, v47
	v_cvt_pk_bf16_f32 v34, v40, v41
	v_cvt_pk_bf16_f32 v35, v42, v43
	global_store_dwordx4 v[52:53], v[32:35], off
	s_mov_b64 s[0:1], 0x50000
	s_nop 0
	v_cvt_pk_bf16_f32 v32, v36, v37
	v_cvt_pk_bf16_f32 v33, v38, v39
	v_cvt_pk_bf16_f32 v34, v48, v49
	v_cvt_pk_bf16_f32 v35, v54, v55
	global_store_dwordx4 v[50:51], v[32:35], off
	s_nop 0
	s_waitcnt vmcnt(13)
	v_pk_mul_f32 v[30:31], v[30:31], v[202:203] op_sel_hi:[1,0]
	v_lshl_add_u64 v[34:35], v[144:145], 0, s[0:1]
	v_lshl_add_u64 v[36:37], s[54:55], 0, v[34:35]
	v_lshl_add_u64 v[34:35], s[2:3], 0, v[34:35]
	v_lshl_add_u64 v[36:37], v[36:37], 0, v[142:143]
	v_lshl_add_u64 v[34:35], v[34:35], 0, v[142:143]
	v_pk_mul_f32 v[28:29], v[28:29], v[202:203] op_sel_hi:[1,0]
	v_pk_mul_f32 v[26:27], v[26:27], v[202:203] op_sel_hi:[1,0]
	v_pk_mul_f32 v[24:25], v[24:25], v[202:203] op_sel_hi:[1,0]
	v_pk_mul_f32 v[22:23], v[22:23], v[202:203] op_sel_hi:[1,0]
	v_pk_mul_f32 v[20:21], v[20:21], v[202:203] op_sel_hi:[1,0]
	v_pk_mul_f32 v[38:39], v[18:19], v[202:203] op_sel_hi:[1,0]
	v_pk_mul_f32 v[32:33], v[16:17], v[202:203] op_sel_hi:[1,0]
	v_cvt_pk_bf16_f32 v16, v28, v29
	v_cvt_pk_bf16_f32 v17, v30, v31
	v_cvt_pk_bf16_f32 v18, v24, v25
	v_cvt_pk_bf16_f32 v19, v26, v27
	global_store_dwordx4 v[36:37], v[16:19], off
	s_mov_b64 s[0:1], 0x58000
	s_nop 0
	v_cvt_pk_bf16_f32 v16, v20, v21
	v_cvt_pk_bf16_f32 v17, v22, v23
	v_cvt_pk_bf16_f32 v18, v32, v33
	v_cvt_pk_bf16_f32 v19, v38, v39
	global_store_dwordx4 v[34:35], v[16:19], off
	s_nop 0
	s_waitcnt vmcnt(14)
	v_pk_mul_f32 v[14:15], v[14:15], v[204:205] op_sel_hi:[1,0]
	v_lshl_add_u64 v[18:19], v[144:145], 0, s[0:1]
	v_lshl_add_u64 v[20:21], s[54:55], 0, v[18:19]
	v_lshl_add_u64 v[18:19], s[2:3], 0, v[18:19]
	v_lshl_add_u64 v[20:21], v[20:21], 0, v[142:143]
	v_lshl_add_u64 v[18:19], v[18:19], 0, v[142:143]
	v_pk_mul_f32 v[12:13], v[12:13], v[204:205] op_sel_hi:[1,0]
	v_pk_mul_f32 v[10:11], v[10:11], v[204:205] op_sel_hi:[1,0]
	v_pk_mul_f32 v[8:9], v[8:9], v[204:205] op_sel_hi:[1,0]
	v_pk_mul_f32 v[6:7], v[6:7], v[204:205] op_sel_hi:[1,0]
	v_pk_mul_f32 v[4:5], v[4:5], v[204:205] op_sel_hi:[1,0]
	v_pk_mul_f32 v[22:23], v[2:3], v[204:205] op_sel_hi:[1,0]
	v_pk_mul_f32 v[16:17], v[0:1], v[204:205] op_sel_hi:[1,0]
	v_cvt_pk_bf16_f32 v0, v12, v13
	v_cvt_pk_bf16_f32 v1, v14, v15
	v_cvt_pk_bf16_f32 v2, v8, v9
	v_cvt_pk_bf16_f32 v3, v10, v11
	s_mov_b64 s[0:1], -1
	global_store_dwordx4 v[20:21], v[0:3], off
	s_nop 1
	v_cvt_pk_bf16_f32 v0, v4, v5
	v_cvt_pk_bf16_f32 v1, v6, v7
	v_cvt_pk_bf16_f32 v2, v16, v17
	v_cvt_pk_bf16_f32 v3, v22, v23
	global_store_dwordx4 v[18:19], v[0:3], off
	s_cbranch_scc1 .LBB0_531
	s_andn2_b64 vcc, exec, s[8:9]
	s_cbranch_vccnz .LBB0_530
	s_barrier
	s_branch .LBB0_530

; __device__ __forceinline__ unsigned cvt_pk_bf16(float lo, float hi) { unsigned r; asm volatile("v_cvt_pk_bf16_f32 %0, %1, %2" : "=v"(r) : "v"(lo), "v"(hi)); return r; }
; __device__ __forceinline__ float bflo(unsigned w) { return __uint_as_float(w << 16); }
; __device__ __forceinline__ float bfhi(unsigned w) { return __uint_as_float(w & 0xffff0000u); }
;     __device__ __forceinline__ void operator()(const f32x4 (&acc)[2][2][4][2], const Unit& u, int wr, int wc, int fr, int fq) const {
;         const int row0 = u.pm * BM + wr * 64 + fr, col0 = u.pn * BM + wc * 32 + 8 * fq;
; #pragma unroll
;         for (int ai = 0; ai < 2; ++ai)
; #pragma unroll
;             for (int m = 0; m < 4; ++m) { const size_t r = (size_t)(row0 + ai * HALF + m * 16);
; #pragma unroll
;                 for (int bj = 0; bj < 2; ++bj) { const u32x4 b = *(const u32x4*)(gates + r * 4096 + 2048 + col0 + bj * HALF);
;                     const f32x4 v0 = acc[ai][bj][m][0], v1 = acc[ai][bj][m][1];
;                     u32x4 w; w.x = cvt_pk_bf16(v0[0] * bflo(b[0]), v0[1] * bfhi(b[0])); w.y = cvt_pk_bf16(v0[2] * bflo(b[1]), v0[3] * bfhi(b[1]));
;                     w.z = cvt_pk_bf16(v1[0] * bflo(b[2]), v1[1] * bfhi(b[2])); w.w = cvt_pk_bf16(v1[2] * bflo(b[3]), v1[3] * bfhi(b[3]));
;                     *(u32x4*)(O + r * 2048 + col0 + bj * HALF) = w; }
;                 asm volatile("" ::: "memory"); }
;     }
.LBB0_708:
	v_ashrrev_i32_e32 v149, 31, v148
	v_ashrrev_i32_e32 v151, 31, v150
	v_lshlrev_b64 v[152:153], 13, v[148:149]
	v_lshl_add_u64 v[152:153], s[18:19], 0, v[152:153]
	v_lshlrev_b64 v[150:151], 1, v[150:151]
	v_lshl_add_u64 v[152:153], v[152:153], 0, v[150:151]
	s_mov_b64 s[0:1], 0x1000
	v_lshl_add_u64 v[162:163], v[152:153], 0, s[0:1]
	v_lshlrev_b64 v[154:155], 12, v[148:149]
	v_lshl_add_u64 v[154:155], s[54:55], 0, v[154:155]
	v_lshl_add_u64 v[154:155], v[154:155], 0, v[150:151]
	global_load_dwordx4 v[164:167], v[162:163], off
	global_load_dwordx4 v[168:171], v[162:163], off offset:256
	s_mov_b64 s[0:1], 0x20000
	v_lshl_add_u64 v[162:163], v[162:163], 0, s[0:1]
	global_load_dwordx4 v[172:175], v[162:163], off
	global_load_dwordx4 v[176:179], v[162:163], off offset:256
	s_mov_b64 s[0:1], 0x20000
	v_lshl_add_u64 v[162:163], v[162:163], 0, s[0:1]
	global_load_dwordx4 v[180:183], v[162:163], off
	global_load_dwordx4 v[184:187], v[162:163], off offset:256
	s_mov_b64 s[0:1], 0x20000
	v_lshl_add_u64 v[162:163], v[162:163], 0, s[0:1]
	global_load_dwordx4 v[190:193], v[162:163], off
	global_load_dwordx4 v[194:197], v[162:163], off offset:256
	s_mov_b64 s[0:1], 0xa0000
	v_lshl_add_u64 v[162:163], v[162:163], 0, s[0:1]
	global_load_dwordx4 v[198:201], v[162:163], off
	global_load_dwordx4 v[202:205], v[162:163], off offset:256
	s_mov_b64 s[0:1], 0x20000
	v_lshl_add_u64 v[162:163], v[162:163], 0, s[0:1]
	global_load_dwordx4 v[206:209], v[162:163], off
	global_load_dwordx4 v[214:217], v[162:163], off offset:256
	s_mov_b64 s[0:1], 0x20000
	v_lshl_add_u64 v[162:163], v[162:163], 0, s[0:1]
	global_load_dwordx4 v[218:221], v[162:163], off
	global_load_dwordx4 v[222:225], v[162:163], off offset:256
	s_mov_b64 s[0:1], 0x20000
	v_lshl_add_u64 v[162:163], v[162:163], 0, s[0:1]
	global_load_dwordx4 v[226:229], v[162:163], off
	global_load_dwordx4 v[230:233], v[162:163], off offset:256
	s_waitcnt vmcnt(15)
	v_lshlrev_b32_e32 v234, 16, v164
	v_and_b32_e32 v235, 0xffff0000, v164
	v_lshlrev_b32_e32 v164, 16, v165
	v_and_b32_e32 v165, 0xffff0000, v165
	v_lshlrev_b32_e32 v236, 16, v166
	v_and_b32_e32 v237, 0xffff0000, v166
	v_lshlrev_b32_e32 v166, 16, v167
	v_and_b32_e32 v167, 0xffff0000, v167
	v_pk_mul_f32 v[124:125], v[124:125], v[234:235]
	v_pk_mul_f32 v[126:127], v[126:127], v[164:165]
	v_pk_mul_f32 v[120:121], v[120:121], v[236:237]
	v_pk_mul_f32 v[122:123], v[122:123], v[166:167]
	v_cvt_pk_bf16_f32 v124, v124, v125
	v_cvt_pk_bf16_f32 v125, v126, v127
	v_cvt_pk_bf16_f32 v126, v120, v121
	v_cvt_pk_bf16_f32 v127, v122, v123
	global_store_dwordx4 v[154:155], v[124:127], off sc1
	s_waitcnt vmcnt(15)
	v_lshlrev_b32_e32 v238, 16, v168
	v_and_b32_e32 v239, 0xffff0000, v168
	v_lshlrev_b32_e32 v168, 16, v169
	v_and_b32_e32 v169, 0xffff0000, v169
	v_lshlrev_b32_e32 v240, 16, v170
	v_and_b32_e32 v241, 0xffff0000, v170
	v_lshlrev_b32_e32 v170, 16, v171
	v_and_b32_e32 v171, 0xffff0000, v171
	v_pk_mul_f32 v[88:89], v[88:89], v[238:239]
	v_pk_mul_f32 v[90:91], v[90:91], v[168:169]
	v_pk_mul_f32 v[92:93], v[92:93], v[240:241]
	v_pk_mul_f32 v[94:95], v[94:95], v[170:171]
	v_cvt_pk_bf16_f32 v88, v88, v89
	v_cvt_pk_bf16_f32 v89, v90, v91
	v_cvt_pk_bf16_f32 v90, v92, v93
	v_cvt_pk_bf16_f32 v91, v94, v95
	global_store_dwordx4 v[154:155], v[88:91], off offset:256 sc1
	s_mov_b64 s[0:1], 0x10000
	v_lshl_add_u64 v[154:155], v[154:155], 0, s[0:1]
	s_waitcnt vmcnt(15)
	v_lshlrev_b32_e32 v234, 16, v172
	v_and_b32_e32 v235, 0xffff0000, v172
	v_lshlrev_b32_e32 v172, 16, v173
	v_and_b32_e32 v173, 0xffff0000, v173
	v_lshlrev_b32_e32 v236, 16, v174
	v_and_b32_e32 v237, 0xffff0000, v174
	v_lshlrev_b32_e32 v174, 16, v175
	v_and_b32_e32 v175, 0xffff0000, v175
	v_pk_mul_f32 v[116:117], v[116:117], v[234:235]
	v_pk_mul_f32 v[118:119], v[118:119], v[172:173]
	v_pk_mul_f32 v[112:113], v[112:113], v[236:237]
	v_pk_mul_f32 v[114:115], v[114:115], v[174:175]
	v_cvt_pk_bf16_f32 v116, v116, v117
	v_cvt_pk_bf16_f32 v117, v118, v119
	v_cvt_pk_bf16_f32 v118, v112, v113
	v_cvt_pk_bf16_f32 v119, v114, v115
	global_store_dwordx4 v[154:155], v[116:119], off sc1
	s_waitcnt vmcnt(15)
	v_lshlrev_b32_e32 v238, 16, v176
	v_and_b32_e32 v239, 0xffff0000, v176
	v_lshlrev_b32_e32 v176, 16, v177
	v_and_b32_e32 v177, 0xffff0000, v177
	v_lshlrev_b32_e32 v240, 16, v178
	v_and_b32_e32 v241, 0xffff0000, v178
	v_lshlrev_b32_e32 v178, 16, v179
	v_and_b32_e32 v179, 0xffff0000, v179
	v_pk_mul_f32 v[80:81], v[80:81], v[238:239]
	v_pk_mul_f32 v[82:83], v[82:83], v[176:177]
	v_pk_mul_f32 v[84:85], v[84:85], v[240:241]
	v_pk_mul_f32 v[86:87], v[86:87], v[178:179]
	v_cvt_pk_bf16_f32 v80, v80, v81
	v_cvt_pk_bf16_f32 v81, v82, v83
	v_cvt_pk_bf16_f32 v82, v84, v85
	v_cvt_pk_bf16_f32 v83, v86, v87
	global_store_dwordx4 v[154:155], v[80:83], off offset:256 sc1
	s_mov_b64 s[0:1], 0x10000
	v_lshl_add_u64 v[154:155], v[154:155], 0, s[0:1]
	s_waitcnt vmcnt(15)
	v_lshlrev_b32_e32 v234, 16, v180
	v_and_b32_e32 v235, 0xffff0000, v180
	v_lshlrev_b32_e32 v180, 16, v181
	v_and_b32_e32 v181, 0xffff0000, v181
	v_lshlrev_b32_e32 v236, 16, v182
	v_and_b32_e32 v237, 0xffff0000, v182
	v_lshlrev_b32_e32 v182, 16, v183
	v_and_b32_e32 v183, 0xffff0000, v183
	v_pk_mul_f32 v[108:109], v[108:109], v[234:235]
	v_pk_mul_f32 v[110:111], v[110:111], v[180:181]
	v_pk_mul_f32 v[104:105], v[104:105], v[236:237]
	v_pk_mul_f32 v[106:107], v[106:107], v[182:183]
	v_cvt_pk_bf16_f32 v108, v108, v109
	v_cvt_pk_bf16_f32 v109, v110, v111
	v_cvt_pk_bf16_f32 v110, v104, v105
	v_cvt_pk_bf16_f32 v111, v106, v107
	global_store_dwordx4 v[154:155], v[108:111], off sc1
	s_waitcnt vmcnt(15)
; __device__ __forceinline__ unsigned cvt_pk_bf16(float lo, float hi) { unsigned r; asm volatile("v_cvt_pk_bf16_f32 %0, %1, %2" : "=v"(r) : "v"(lo), "v"(hi)); return r; }
; __device__ __forceinline__ float bflo(unsigned w) { return __uint_as_float(w << 16); }
; __device__ __forceinline__ float bfhi(unsigned w) { return __uint_as_float(w & 0xffff0000u); }
;     __device__ __forceinline__ void operator()(const f32x4 (&acc)[2][2][4][2], const Unit& u, int wr, int wc, int fr, int fq) const {
;     ...
;         for (int ai = 0; ai < 2; ++ai)
; #pragma unroll
;             for (int m = 0; m < 4; ++m) { const size_t r = (size_t)(row0 + ai * HALF + m * 16);
; #pragma unroll
;                 for (int bj = 0; bj < 2; ++bj) { const u32x4 b = *(const u32x4*)(gates + r * 4096 + 2048 + col0 + bj * HALF);
;                     const f32x4 v0 = acc[ai][bj][m][0], v1 = acc[ai][bj][m][1];
;                     u32x4 w; w.x = cvt_pk_bf16(v0[0] * bflo(b[0]), v0[1] * bfhi(b[0])); w.y = cvt_pk_bf16(v0[2] * bflo(b[1]), v0[3] * bfhi(b[1]));
;                     w.z = cvt_pk_bf16(v1[0] * bflo(b[2]), v1[1] * bfhi(b[2])); w.w = cvt_pk_bf16(v1[2] * bflo(b[3]), v1[3] * bfhi(b[3]));
;                     *(u32x4*)(O + r * 2048 + col0 + bj * HALF) = w; }
;                 asm volatile("" ::: "memory"); }
	v_lshlrev_b32_e32 v238, 16, v184
	v_and_b32_e32 v239, 0xffff0000, v184
	v_lshlrev_b32_e32 v184, 16, v185
	v_and_b32_e32 v185, 0xffff0000, v185
	v_lshlrev_b32_e32 v240, 16, v186
	v_and_b32_e32 v241, 0xffff0000, v186
	v_lshlrev_b32_e32 v186, 16, v187
	v_and_b32_e32 v187, 0xffff0000, v187
	v_pk_mul_f32 v[72:73], v[72:73], v[238:239]
	v_pk_mul_f32 v[74:75], v[74:75], v[184:185]
	v_pk_mul_f32 v[76:77], v[76:77], v[240:241]
	v_pk_mul_f32 v[78:79], v[78:79], v[186:187]
	v_cvt_pk_bf16_f32 v72, v72, v73
	v_cvt_pk_bf16_f32 v73, v74, v75
	v_cvt_pk_bf16_f32 v74, v76, v77
	v_cvt_pk_bf16_f32 v75, v78, v79
	global_store_dwordx4 v[154:155], v[72:75], off offset:256 sc1
	s_mov_b64 s[0:1], 0x10000
	v_lshl_add_u64 v[154:155], v[154:155], 0, s[0:1]
	s_waitcnt vmcnt(15)
	v_lshlrev_b32_e32 v234, 16, v190
	v_and_b32_e32 v235, 0xffff0000, v190
	v_lshlrev_b32_e32 v190, 16, v191
	v_and_b32_e32 v191, 0xffff0000, v191
	v_lshlrev_b32_e32 v236, 16, v192
	v_and_b32_e32 v237, 0xffff0000, v192
	v_lshlrev_b32_e32 v192, 16, v193
	v_and_b32_e32 v193, 0xffff0000, v193
	v_pk_mul_f32 v[100:101], v[100:101], v[234:235]
	v_pk_mul_f32 v[102:103], v[102:103], v[190:191]
	v_pk_mul_f32 v[96:97], v[96:97], v[236:237]
	v_pk_mul_f32 v[98:99], v[98:99], v[192:193]
	v_cvt_pk_bf16_f32 v100, v100, v101
	v_cvt_pk_bf16_f32 v101, v102, v103
	v_cvt_pk_bf16_f32 v102, v96, v97
	v_cvt_pk_bf16_f32 v103, v98, v99
	global_store_dwordx4 v[154:155], v[100:103], off sc1
	s_waitcnt vmcnt(15)
	v_lshlrev_b32_e32 v238, 16, v194
	v_and_b32_e32 v239, 0xffff0000, v194
	v_lshlrev_b32_e32 v194, 16, v195
	v_and_b32_e32 v195, 0xffff0000, v195
	v_lshlrev_b32_e32 v240, 16, v196
	v_and_b32_e32 v241, 0xffff0000, v196
	v_lshlrev_b32_e32 v196, 16, v197
	v_and_b32_e32 v197, 0xffff0000, v197
	v_pk_mul_f32 v[64:65], v[64:65], v[238:239]
	v_pk_mul_f32 v[66:67], v[66:67], v[194:195]
	v_pk_mul_f32 v[68:69], v[68:69], v[240:241]
	v_pk_mul_f32 v[70:71], v[70:71], v[196:197]
	v_cvt_pk_bf16_f32 v64, v64, v65
	v_cvt_pk_bf16_f32 v65, v66, v67
	v_cvt_pk_bf16_f32 v66, v68, v69
	v_cvt_pk_bf16_f32 v67, v70, v71
	global_store_dwordx4 v[154:155], v[64:67], off offset:256 sc1
	s_mov_b64 s[0:1], 0x50000
	v_lshl_add_u64 v[154:155], v[154:155], 0, s[0:1]
	s_waitcnt vmcnt(15)
	v_lshlrev_b32_e32 v234, 16, v198
	v_and_b32_e32 v235, 0xffff0000, v198
	v_lshlrev_b32_e32 v198, 16, v199
	v_and_b32_e32 v199, 0xffff0000, v199
	v_lshlrev_b32_e32 v236, 16, v200
	v_and_b32_e32 v237, 0xffff0000, v200
	v_lshlrev_b32_e32 v200, 16, v201
	v_and_b32_e32 v201, 0xffff0000, v201
	v_pk_mul_f32 v[60:61], v[60:61], v[234:235]
	v_pk_mul_f32 v[62:63], v[62:63], v[198:199]
	v_pk_mul_f32 v[56:57], v[56:57], v[236:237]
	v_pk_mul_f32 v[58:59], v[58:59], v[200:201]
	v_cvt_pk_bf16_f32 v60, v60, v61
	v_cvt_pk_bf16_f32 v61, v62, v63
	v_cvt_pk_bf16_f32 v62, v56, v57
	v_cvt_pk_bf16_f32 v63, v58, v59
	global_store_dwordx4 v[154:155], v[60:63], off sc1
	s_waitcnt vmcnt(15)
	v_lshlrev_b32_e32 v238, 16, v202
	v_and_b32_e32 v239, 0xffff0000, v202
	v_lshlrev_b32_e32 v202, 16, v203
	v_and_b32_e32 v203, 0xffff0000, v203
	v_lshlrev_b32_e32 v240, 16, v204
	v_and_b32_e32 v241, 0xffff0000, v204
	v_lshlrev_b32_e32 v204, 16, v205
	v_and_b32_e32 v205, 0xffff0000, v205
	v_pk_mul_f32 v[52:53], v[52:53], v[238:239]
	v_pk_mul_f32 v[54:55], v[54:55], v[202:203]
	v_pk_mul_f32 v[48:49], v[48:49], v[240:241]
	v_pk_mul_f32 v[50:51], v[50:51], v[204:205]
	v_cvt_pk_bf16_f32 v52, v52, v53
	v_cvt_pk_bf16_f32 v53, v54, v55
	v_cvt_pk_bf16_f32 v54, v48, v49
	v_cvt_pk_bf16_f32 v55, v50, v51
	global_store_dwordx4 v[154:155], v[52:55], off offset:256 sc1
	s_mov_b64 s[0:1], 0x10000
	v_lshl_add_u64 v[154:155], v[154:155], 0, s[0:1]
	s_waitcnt vmcnt(15)
	v_lshlrev_b32_e32 v234, 16, v206
	v_and_b32_e32 v235, 0xffff0000, v206
	v_lshlrev_b32_e32 v206, 16, v207
	v_and_b32_e32 v207, 0xffff0000, v207
	v_lshlrev_b32_e32 v236, 16, v208
	v_and_b32_e32 v237, 0xffff0000, v208
	v_lshlrev_b32_e32 v208, 16, v209
	v_and_b32_e32 v209, 0xffff0000, v209
	v_pk_mul_f32 v[44:45], v[44:45], v[234:235]
	v_pk_mul_f32 v[46:47], v[46:47], v[206:207]
	v_pk_mul_f32 v[40:41], v[40:41], v[236:237]
	v_pk_mul_f32 v[42:43], v[42:43], v[208:209]
	v_cvt_pk_bf16_f32 v44, v44, v45
	v_cvt_pk_bf16_f32 v45, v46, v47
	v_cvt_pk_bf16_f32 v46, v40, v41
	v_cvt_pk_bf16_f32 v47, v42, v43
	global_store_dwordx4 v[154:155], v[44:47], off sc1
	s_waitcnt vmcnt(15)
; __device__ __forceinline__ unsigned cvt_pk_bf16(float lo, float hi) { unsigned r; asm volatile("v_cvt_pk_bf16_f32 %0, %1, %2" : "=v"(r) : "v"(lo), "v"(hi)); return r; }
; __device__ __forceinline__ float bflo(unsigned w) { return __uint_as_float(w << 16); }
; __device__ __forceinline__ float bfhi(unsigned w) { return __uint_as_float(w & 0xffff0000u); }
;     __device__ __forceinline__ void operator()(const f32x4 (&acc)[2][2][4][2], const Unit& u, int wr, int wc, int fr, int fq) const {
;     ...
;         for (int ai = 0; ai < 2; ++ai)
; #pragma unroll
;             for (int m = 0; m < 4; ++m) { const size_t r = (size_t)(row0 + ai * HALF + m * 16);
; #pragma unroll
;                 for (int bj = 0; bj < 2; ++bj) { const u32x4 b = *(const u32x4*)(gates + r * 4096 + 2048 + col0 + bj * HALF);
;                     const f32x4 v0 = acc[ai][bj][m][0], v1 = acc[ai][bj][m][1];
;                     u32x4 w; w.x = cvt_pk_bf16(v0[0] * bflo(b[0]), v0[1] * bfhi(b[0])); w.y = cvt_pk_bf16(v0[2] * bflo(b[1]), v0[3] * bfhi(b[1]));
;                     w.z = cvt_pk_bf16(v1[0] * bflo(b[2]), v1[1] * bfhi(b[2])); w.w = cvt_pk_bf16(v1[2] * bflo(b[3]), v1[3] * bfhi(b[3]));
;                     *(u32x4*)(O + r * 2048 + col0 + bj * HALF) = w; }
;                 asm volatile("" ::: "memory"); }
;     }
	v_lshlrev_b32_e32 v238, 16, v214
	v_and_b32_e32 v239, 0xffff0000, v214
	v_lshlrev_b32_e32 v214, 16, v215
	v_and_b32_e32 v215, 0xffff0000, v215
	v_lshlrev_b32_e32 v240, 16, v216
	v_and_b32_e32 v241, 0xffff0000, v216
	v_lshlrev_b32_e32 v216, 16, v217
	v_and_b32_e32 v217, 0xffff0000, v217
	v_pk_mul_f32 v[36:37], v[36:37], v[238:239]
	v_pk_mul_f32 v[38:39], v[38:39], v[214:215]
	v_pk_mul_f32 v[32:33], v[32:33], v[240:241]
	v_pk_mul_f32 v[34:35], v[34:35], v[216:217]
	v_cvt_pk_bf16_f32 v36, v36, v37
	v_cvt_pk_bf16_f32 v37, v38, v39
	v_cvt_pk_bf16_f32 v38, v32, v33
	v_cvt_pk_bf16_f32 v39, v34, v35
	global_store_dwordx4 v[154:155], v[36:39], off offset:256 sc1
	s_mov_b64 s[0:1], 0x10000
	v_lshl_add_u64 v[154:155], v[154:155], 0, s[0:1]
	s_waitcnt vmcnt(15)
	v_lshlrev_b32_e32 v234, 16, v218
	v_and_b32_e32 v235, 0xffff0000, v218
	v_lshlrev_b32_e32 v218, 16, v219
	v_and_b32_e32 v219, 0xffff0000, v219
	v_lshlrev_b32_e32 v236, 16, v220
	v_and_b32_e32 v237, 0xffff0000, v220
	v_lshlrev_b32_e32 v220, 16, v221
	v_and_b32_e32 v221, 0xffff0000, v221
	v_pk_mul_f32 v[28:29], v[28:29], v[234:235]
	v_pk_mul_f32 v[30:31], v[30:31], v[218:219]
	v_pk_mul_f32 v[24:25], v[24:25], v[236:237]
	v_pk_mul_f32 v[26:27], v[26:27], v[220:221]
	v_cvt_pk_bf16_f32 v28, v28, v29
	v_cvt_pk_bf16_f32 v29, v30, v31
	v_cvt_pk_bf16_f32 v30, v24, v25
	v_cvt_pk_bf16_f32 v31, v26, v27
	global_store_dwordx4 v[154:155], v[28:31], off sc1
	s_waitcnt vmcnt(15)
	v_lshlrev_b32_e32 v238, 16, v222
	v_and_b32_e32 v239, 0xffff0000, v222
	v_lshlrev_b32_e32 v222, 16, v223
	v_and_b32_e32 v223, 0xffff0000, v223
	v_lshlrev_b32_e32 v240, 16, v224
	v_and_b32_e32 v241, 0xffff0000, v224
	v_lshlrev_b32_e32 v224, 16, v225
	v_and_b32_e32 v225, 0xffff0000, v225
	v_pk_mul_f32 v[20:21], v[20:21], v[238:239]
	v_pk_mul_f32 v[22:23], v[22:23], v[222:223]
	v_pk_mul_f32 v[16:17], v[16:17], v[240:241]
	v_pk_mul_f32 v[18:19], v[18:19], v[224:225]
	v_cvt_pk_bf16_f32 v20, v20, v21
	v_cvt_pk_bf16_f32 v21, v22, v23
	v_cvt_pk_bf16_f32 v22, v16, v17
	v_cvt_pk_bf16_f32 v23, v18, v19
	global_store_dwordx4 v[154:155], v[20:23], off offset:256 sc1
	s_mov_b64 s[0:1], 0x10000
	v_lshl_add_u64 v[154:155], v[154:155], 0, s[0:1]
	s_waitcnt vmcnt(15)
	v_lshlrev_b32_e32 v234, 16, v226
	v_and_b32_e32 v235, 0xffff0000, v226
	v_lshlrev_b32_e32 v226, 16, v227
	v_and_b32_e32 v227, 0xffff0000, v227
	v_lshlrev_b32_e32 v236, 16, v228
	v_and_b32_e32 v237, 0xffff0000, v228
	v_lshlrev_b32_e32 v228, 16, v229
	v_and_b32_e32 v229, 0xffff0000, v229
	v_pk_mul_f32 v[12:13], v[12:13], v[234:235]
	v_pk_mul_f32 v[14:15], v[14:15], v[226:227]
	v_pk_mul_f32 v[8:9], v[8:9], v[236:237]
	v_pk_mul_f32 v[10:11], v[10:11], v[228:229]
	v_cvt_pk_bf16_f32 v12, v12, v13
	v_cvt_pk_bf16_f32 v13, v14, v15
	v_cvt_pk_bf16_f32 v14, v8, v9
	v_cvt_pk_bf16_f32 v15, v10, v11
	global_store_dwordx4 v[154:155], v[12:15], off sc1
	s_waitcnt vmcnt(15)
	v_lshlrev_b32_e32 v238, 16, v230
	v_and_b32_e32 v239, 0xffff0000, v230
	v_lshlrev_b32_e32 v230, 16, v231
	v_and_b32_e32 v231, 0xffff0000, v231
	v_lshlrev_b32_e32 v240, 16, v232
	v_and_b32_e32 v241, 0xffff0000, v232
	v_lshlrev_b32_e32 v232, 16, v233
	v_and_b32_e32 v233, 0xffff0000, v233
	v_pk_mul_f32 v[4:5], v[4:5], v[238:239]
	v_pk_mul_f32 v[6:7], v[6:7], v[230:231]
	v_pk_mul_f32 v[0:1], v[0:1], v[240:241]
	v_pk_mul_f32 v[2:3], v[2:3], v[232:233]
	v_cvt_pk_bf16_f32 v4, v4, v5
	v_cvt_pk_bf16_f32 v5, v6, v7
	v_cvt_pk_bf16_f32 v6, v0, v1
	v_cvt_pk_bf16_f32 v7, v2, v3
	global_store_dwordx4 v[154:155], v[4:7], off offset:256 sc1
	s_mov_b64 s[0:1], -1
	s_andn2_b64 vcc, exec, s[2:3]
	s_cbranch_vccnz .LBB0_695
	s_andn2_b64 vcc, exec, s[6:7]
	s_cbranch_vccnz .LBB0_694
	s_barrier
	s_branch .LBB0_694

; __device__ __forceinline__ unsigned cvt_pk_bf16(float lo, float hi) { unsigned r; asm volatile("v_cvt_pk_bf16_f32 %0, %1, %2" : "=v"(r) : "v"(lo), "v"(hi)); return r; }
; __device__ __forceinline__ float bflo(unsigned w) { return __uint_as_float(w << 16); }
; __device__ __forceinline__ float bfhi(unsigned w) { return __uint_as_float(w & 0xffff0000u); }
;     __device__ __forceinline__ void operator()(const f32x4 (&acc)[2][2][4][2], const Unit& u, int wr, int wc, int fr, int fq) const {
;         const int row0 = u.pm * BM + wr * 64 + fr, col0 = u.pn * BM + wc * 32 + 8 * fq;
;         const float* gb = g + (size_t)(u.pm >> 3) * 12288 + col0;
;         f32x4 gv[2][2];
; #pragma unroll
;         for (int bj = 0; bj < 2; ++bj)
; #pragma unroll
;             for (int n = 0; n < 2; ++n) gv[bj][n] = *(const f32x4*)(gb + bj * HALF + n * 4);
; #pragma unroll
;         for (int ai = 0; ai < 2; ++ai)
; #pragma unroll
;             for (int m = 0; m < 4; ++m) { const size_t off = (size_t)(row0 + ai * HALF + m * 16) * 2048 + col0;
; #pragma unroll
;                 for (int bj = 0; bj < 2; ++bj) { f32x4 b0, b1;
;                     if constexpr (sizeof(TB) == 4) { b0 = __builtin_nontemporal_load((const f32x4*)((const float*)base + off + bj * HALF)); b1 = __builtin_nontemporal_load((const f32x4*)((const float*)base + off + bj * HALF + 4)); }
;                     else { const u32x4 t = *(const u32x4*)((const bf16_t*)base + off + bj * HALF);
;                         b0[0] = bflo(t[0]); b0[1] = bfhi(t[0]); b0[2] = bflo(t[1]); b0[3] = bfhi(t[1]); b1[0] = bflo(t[2]); b1[1] = bfhi(t[2]); b1[2] = bflo(t[3]); b1[3] = bfhi(t[3]); }
;                     const f32x4 v0 = b0 + gv[bj][0] * acc[ai][bj][m][0], v1 = b1 + gv[bj][1] * acc[ai][bj][m][1];
;                     u32x4 w; w.x = cvt_pk_bf16(v0[0], v0[1]); w.y = cvt_pk_bf16(v0[2], v0[3]); w.z = cvt_pk_bf16(v1[0], v1[1]); w.w = cvt_pk_bf16(v1[2], v1[3]);
;                     *(u32x4*)(out + off + bj * HALF) = w; } }
.LBB0_784:
	v_lshl_add_u32 v164, s60, 8, v166
	v_lshl_or_b32 v162, s70, 8, v168
	s_ashr_i32 s0, s60, 3
	v_ashrrev_i32_e32 v165, 31, v164
	s_mul_hi_i32 s1, s0, 0xc000
	s_mul_i32 s0, s0, 0xc000
	v_ashrrev_i32_e32 v163, 31, v162
	v_lshlrev_b64 v[128:129], 11, v[164:165]
	s_add_u32 s0, s33, s0
	v_lshl_add_u64 v[160:161], v[128:129], 0, v[162:163]
	s_addc_u32 s1, s61, s1
	v_lshl_add_u64 v[180:181], v[160:161], 2, s[52:53]
	v_lshl_add_u64 v[132:133], v[162:163], 2, s[0:1]
	v_lshl_add_u64 v[182:183], v[160:161], 1, s[72:73]
	global_load_dwordx4 v[172:175], v[180:181], off nt
	global_load_dwordx4 v[176:179], v[180:181], off offset:16 nt
	global_load_dwordx4 v[184:187], v[180:181], off offset:512 nt
	global_load_dwordx4 v[160:163], v[180:181], off offset:528 nt
	s_mov_b64 s[0:1], 0x20000
	v_lshl_add_u64 v[180:181], v[180:181], 0, s[0:1]
	global_load_dwordx4 v[140:143], v[132:133], off
	global_load_dwordx4 v[136:139], v[132:133], off offset:16
	global_load_dwordx4 v[128:131], v[132:133], off offset:528
	global_load_dwordx4 v[132:135], v[132:133], off offset:512
	global_load_dwordx4 v[190:193], v[180:181], off nt
	global_load_dwordx4 v[194:197], v[180:181], off offset:16 nt
	global_load_dwordx4 v[198:201], v[180:181], off offset:512 nt
	global_load_dwordx4 v[202:205], v[180:181], off offset:528 nt
	s_mov_b64 s[0:1], 0x20000
	v_lshl_add_u64 v[180:181], v[180:181], 0, s[0:1]
	global_load_dwordx4 v[206:209], v[180:181], off nt
	global_load_dwordx4 v[214:217], v[180:181], off offset:16 nt
	global_load_dwordx4 v[218:221], v[180:181], off offset:512 nt
	global_load_dwordx4 v[222:225], v[180:181], off offset:528 nt
	s_mov_b64 s[0:1], 0x20000
	v_lshl_add_u64 v[180:181], v[180:181], 0, s[0:1]
	global_load_dwordx4 v[226:229], v[180:181], off nt
	global_load_dwordx4 v[230:233], v[180:181], off offset:16 nt
	global_load_dwordx4 v[234:237], v[180:181], off offset:512 nt
	global_load_dwordx4 v[238:241], v[180:181], off offset:528 nt
	s_mov_b64 s[0:1], 0xa0000
	v_lshl_add_u64 v[180:181], v[180:181], 0, s[0:1]
	s_waitcnt vmcnt(12)
	s_waitcnt vmcnt(18)
	v_pk_fma_f32 v[124:125], v[124:125], v[140:141], v[172:173]
	v_pk_fma_f32 v[126:127], v[126:127], v[142:143], v[174:175]
	v_pk_fma_f32 v[120:121], v[120:121], v[136:137], v[176:177]
	v_pk_fma_f32 v[122:123], v[122:123], v[138:139], v[178:179]
	v_cvt_pk_bf16_f32 v124, v124, v125
	v_cvt_pk_bf16_f32 v125, v126, v127
	v_cvt_pk_bf16_f32 v126, v120, v121
	v_cvt_pk_bf16_f32 v127, v122, v123
	global_store_dwordx4 v[182:183], v[124:127], off sc1
	s_waitcnt vmcnt(17)
	v_pk_fma_f32 v[116:117], v[116:117], v[132:133], v[184:185]
	v_pk_fma_f32 v[118:119], v[118:119], v[134:135], v[186:187]
	v_pk_fma_f32 v[112:113], v[112:113], v[128:129], v[160:161]
	v_pk_fma_f32 v[114:115], v[114:115], v[130:131], v[162:163]
	v_cvt_pk_bf16_f32 v116, v116, v117
	v_cvt_pk_bf16_f32 v117, v118, v119
	v_cvt_pk_bf16_f32 v118, v112, v113
	v_cvt_pk_bf16_f32 v119, v114, v115
	global_store_dwordx4 v[182:183], v[116:119], off offset:256 sc1
	s_mov_b64 s[0:1], 0x10000
	v_lshl_add_u64 v[182:183], v[182:183], 0, s[0:1]
	global_load_dwordx4 v[172:175], v[180:181], off nt
	global_load_dwordx4 v[176:179], v[180:181], off offset:16 nt
	global_load_dwordx4 v[184:187], v[180:181], off offset:512 nt
	global_load_dwordx4 v[160:163], v[180:181], off offset:528 nt
	s_mov_b64 s[0:1], 0x20000
	v_lshl_add_u64 v[180:181], v[180:181], 0, s[0:1]
	s_waitcnt vmcnt(16)
	v_pk_fma_f32 v[108:109], v[108:109], v[140:141], v[190:191]
	v_pk_fma_f32 v[110:111], v[110:111], v[142:143], v[192:193]
	v_pk_fma_f32 v[104:105], v[104:105], v[136:137], v[194:195]
	v_pk_fma_f32 v[106:107], v[106:107], v[138:139], v[196:197]
	v_cvt_pk_bf16_f32 v108, v108, v109
	v_cvt_pk_bf16_f32 v109, v110, v111
	v_cvt_pk_bf16_f32 v110, v104, v105
	v_cvt_pk_bf16_f32 v111, v106, v107
	global_store_dwordx4 v[182:183], v[108:111], off sc1
	s_waitcnt vmcnt(15)
	v_pk_fma_f32 v[100:101], v[100:101], v[132:133], v[198:199]
	v_pk_fma_f32 v[102:103], v[102:103], v[134:135], v[200:201]
	v_pk_fma_f32 v[96:97], v[96:97], v[128:129], v[202:203]
	v_pk_fma_f32 v[98:99], v[98:99], v[130:131], v[204:205]
	v_cvt_pk_bf16_f32 v100, v100, v101
	v_cvt_pk_bf16_f32 v101, v102, v103
	v_cvt_pk_bf16_f32 v102, v96, v97
	v_cvt_pk_bf16_f32 v103, v98, v99
	global_store_dwordx4 v[182:183], v[100:103], off offset:256 sc1
	s_mov_b64 s[0:1], 0x10000
	v_lshl_add_u64 v[182:183], v[182:183], 0, s[0:1]
	global_load_dwordx4 v[190:193], v[180:181], off nt
	global_load_dwordx4 v[194:197], v[180:181], off offset:16 nt
	global_load_dwordx4 v[198:201], v[180:181], off offset:512 nt
	global_load_dwordx4 v[202:205], v[180:181], off offset:528 nt
	s_mov_b64 s[0:1], 0x20000
	v_lshl_add_u64 v[180:181], v[180:181], 0, s[0:1]
	s_waitcnt vmcnt(18)
	v_pk_fma_f32 v[92:93], v[92:93], v[140:141], v[206:207]
	v_pk_fma_f32 v[94:95], v[94:95], v[142:143], v[208:209]
	v_pk_fma_f32 v[88:89], v[88:89], v[136:137], v[214:215]
	v_pk_fma_f32 v[90:91], v[90:91], v[138:139], v[216:217]
	v_cvt_pk_bf16_f32 v92, v92, v93
	v_cvt_pk_bf16_f32 v93, v94, v95
	v_cvt_pk_bf16_f32 v94, v88, v89
	v_cvt_pk_bf16_f32 v95, v90, v91
	global_store_dwordx4 v[182:183], v[92:95], off sc1
	s_waitcnt vmcnt(17)
; __device__ __forceinline__ unsigned cvt_pk_bf16(float lo, float hi) { unsigned r; asm volatile("v_cvt_pk_bf16_f32 %0, %1, %2" : "=v"(r) : "v"(lo), "v"(hi)); return r; }
; __device__ __forceinline__ float bflo(unsigned w) { return __uint_as_float(w << 16); }
; __device__ __forceinline__ float bfhi(unsigned w) { return __uint_as_float(w & 0xffff0000u); }
;     __device__ __forceinline__ void operator()(const f32x4 (&acc)[2][2][4][2], const Unit& u, int wr, int wc, int fr, int fq) const {
;     ...
;             for (int m = 0; m < 4; ++m) { const size_t off = (size_t)(row0 + ai * HALF + m * 16) * 2048 + col0;
; #pragma unroll
;                 for (int bj = 0; bj < 2; ++bj) { f32x4 b0, b1;
;                     if constexpr (sizeof(TB) == 4) { b0 = __builtin_nontemporal_load((const f32x4*)((const float*)base + off + bj * HALF)); b1 = __builtin_nontemporal_load((const f32x4*)((const float*)base + off + bj * HALF + 4)); }
;                     else { const u32x4 t = *(const u32x4*)((const bf16_t*)base + off + bj * HALF);
;                         b0[0] = bflo(t[0]); b0[1] = bfhi(t[0]); b0[2] = bflo(t[1]); b0[3] = bfhi(t[1]); b1[0] = bflo(t[2]); b1[1] = bfhi(t[2]); b1[2] = bflo(t[3]); b1[3] = bfhi(t[3]); }
;                     const f32x4 v0 = b0 + gv[bj][0] * acc[ai][bj][m][0], v1 = b1 + gv[bj][1] * acc[ai][bj][m][1];
;                     u32x4 w; w.x = cvt_pk_bf16(v0[0], v0[1]); w.y = cvt_pk_bf16(v0[2], v0[3]); w.z = cvt_pk_bf16(v1[0], v1[1]); w.w = cvt_pk_bf16(v1[2], v1[3]);
;                     *(u32x4*)(out + off + bj * HALF) = w; } }
	v_pk_fma_f32 v[84:85], v[84:85], v[132:133], v[218:219]
	v_pk_fma_f32 v[86:87], v[86:87], v[134:135], v[220:221]
	v_pk_fma_f32 v[80:81], v[80:81], v[128:129], v[222:223]
	v_pk_fma_f32 v[82:83], v[82:83], v[130:131], v[224:225]
	v_cvt_pk_bf16_f32 v84, v84, v85
	v_cvt_pk_bf16_f32 v85, v86, v87
	v_cvt_pk_bf16_f32 v86, v80, v81
	v_cvt_pk_bf16_f32 v87, v82, v83
	global_store_dwordx4 v[182:183], v[84:87], off offset:256 sc1
	s_mov_b64 s[0:1], 0x10000
	v_lshl_add_u64 v[182:183], v[182:183], 0, s[0:1]
	global_load_dwordx4 v[206:209], v[180:181], off nt
	global_load_dwordx4 v[214:217], v[180:181], off offset:16 nt
	global_load_dwordx4 v[218:221], v[180:181], off offset:512 nt
	global_load_dwordx4 v[222:225], v[180:181], off offset:528 nt
	s_mov_b64 s[0:1], 0x20000
	v_lshl_add_u64 v[180:181], v[180:181], 0, s[0:1]
	s_waitcnt vmcnt(20)
	v_pk_fma_f32 v[76:77], v[76:77], v[140:141], v[226:227]
	v_pk_fma_f32 v[78:79], v[78:79], v[142:143], v[228:229]
	v_pk_fma_f32 v[72:73], v[72:73], v[136:137], v[230:231]
	v_pk_fma_f32 v[74:75], v[74:75], v[138:139], v[232:233]
	v_cvt_pk_bf16_f32 v76, v76, v77
	v_cvt_pk_bf16_f32 v77, v78, v79
	v_cvt_pk_bf16_f32 v78, v72, v73
	v_cvt_pk_bf16_f32 v79, v74, v75
	global_store_dwordx4 v[182:183], v[76:79], off sc1
	s_waitcnt vmcnt(19)
	v_pk_fma_f32 v[68:69], v[68:69], v[132:133], v[234:235]
	v_pk_fma_f32 v[70:71], v[70:71], v[134:135], v[236:237]
	v_pk_fma_f32 v[64:65], v[64:65], v[128:129], v[238:239]
	v_pk_fma_f32 v[66:67], v[66:67], v[130:131], v[240:241]
	v_cvt_pk_bf16_f32 v68, v68, v69
	v_cvt_pk_bf16_f32 v69, v70, v71
	v_cvt_pk_bf16_f32 v70, v64, v65
	v_cvt_pk_bf16_f32 v71, v66, v67
	global_store_dwordx4 v[182:183], v[68:71], off offset:256 sc1
	s_mov_b64 s[0:1], 0x50000
	v_lshl_add_u64 v[182:183], v[182:183], 0, s[0:1]
	global_load_dwordx4 v[226:229], v[180:181], off nt
	global_load_dwordx4 v[230:233], v[180:181], off offset:16 nt
	global_load_dwordx4 v[234:237], v[180:181], off offset:512 nt
	global_load_dwordx4 v[238:241], v[180:181], off offset:528 nt
	s_waitcnt vmcnt(20)
	v_pk_fma_f32 v[60:61], v[60:61], v[140:141], v[172:173]
	v_pk_fma_f32 v[62:63], v[62:63], v[142:143], v[174:175]
	v_pk_fma_f32 v[56:57], v[56:57], v[136:137], v[176:177]
	v_pk_fma_f32 v[58:59], v[58:59], v[138:139], v[178:179]
	v_cvt_pk_bf16_f32 v60, v60, v61
	v_cvt_pk_bf16_f32 v61, v62, v63
	v_cvt_pk_bf16_f32 v62, v56, v57
	v_cvt_pk_bf16_f32 v63, v58, v59
	global_store_dwordx4 v[182:183], v[60:63], off sc1
	s_waitcnt vmcnt(19)
	v_pk_fma_f32 v[52:53], v[52:53], v[132:133], v[184:185]
	v_pk_fma_f32 v[54:55], v[54:55], v[134:135], v[186:187]
	v_pk_fma_f32 v[48:49], v[48:49], v[128:129], v[160:161]
	v_pk_fma_f32 v[50:51], v[50:51], v[130:131], v[162:163]
	v_cvt_pk_bf16_f32 v52, v52, v53
	v_cvt_pk_bf16_f32 v53, v54, v55
	v_cvt_pk_bf16_f32 v54, v48, v49
	v_cvt_pk_bf16_f32 v55, v50, v51
	global_store_dwordx4 v[182:183], v[52:55], off offset:256 sc1
	s_mov_b64 s[0:1], 0x10000
	v_lshl_add_u64 v[182:183], v[182:183], 0, s[0:1]
	s_waitcnt vmcnt(16)
	v_pk_fma_f32 v[44:45], v[44:45], v[140:141], v[190:191]
	v_pk_fma_f32 v[46:47], v[46:47], v[142:143], v[192:193]
	v_pk_fma_f32 v[40:41], v[40:41], v[136:137], v[194:195]
	v_pk_fma_f32 v[42:43], v[42:43], v[138:139], v[196:197]
	v_cvt_pk_bf16_f32 v44, v44, v45
	v_cvt_pk_bf16_f32 v45, v46, v47
	v_cvt_pk_bf16_f32 v46, v40, v41
	v_cvt_pk_bf16_f32 v47, v42, v43
	global_store_dwordx4 v[182:183], v[44:47], off sc1
	s_waitcnt vmcnt(15)
	v_pk_fma_f32 v[36:37], v[36:37], v[132:133], v[198:199]
	v_pk_fma_f32 v[38:39], v[38:39], v[134:135], v[200:201]
	v_pk_fma_f32 v[32:33], v[32:33], v[128:129], v[202:203]
	v_pk_fma_f32 v[34:35], v[34:35], v[130:131], v[204:205]
	v_cvt_pk_bf16_f32 v36, v36, v37
	v_cvt_pk_bf16_f32 v37, v38, v39
	v_cvt_pk_bf16_f32 v38, v32, v33
	v_cvt_pk_bf16_f32 v39, v34, v35
	global_store_dwordx4 v[182:183], v[36:39], off offset:256 sc1
	s_mov_b64 s[0:1], 0x10000
	v_lshl_add_u64 v[182:183], v[182:183], 0, s[0:1]
	s_waitcnt vmcnt(12)
	v_pk_fma_f32 v[28:29], v[28:29], v[140:141], v[206:207]
	v_pk_fma_f32 v[30:31], v[30:31], v[142:143], v[208:209]
	v_pk_fma_f32 v[24:25], v[24:25], v[136:137], v[214:215]
	v_pk_fma_f32 v[26:27], v[26:27], v[138:139], v[216:217]
	v_cvt_pk_bf16_f32 v28, v28, v29
	v_cvt_pk_bf16_f32 v29, v30, v31
	v_cvt_pk_bf16_f32 v30, v24, v25
	v_cvt_pk_bf16_f32 v31, v26, v27
	global_store_dwordx4 v[182:183], v[28:31], off sc1
	s_waitcnt vmcnt(11)
	v_pk_fma_f32 v[20:21], v[20:21], v[132:133], v[218:219]
	v_pk_fma_f32 v[22:23], v[22:23], v[134:135], v[220:221]
	v_pk_fma_f32 v[16:17], v[16:17], v[128:129], v[222:223]
	v_pk_fma_f32 v[18:19], v[18:19], v[130:131], v[224:225]
	v_cvt_pk_bf16_f32 v20, v20, v21
	v_cvt_pk_bf16_f32 v21, v22, v23
	v_cvt_pk_bf16_f32 v22, v16, v17
	v_cvt_pk_bf16_f32 v23, v18, v19
	global_store_dwordx4 v[182:183], v[20:23], off offset:256 sc1
	s_mov_b64 s[0:1], 0x10000
	v_lshl_add_u64 v[182:183], v[182:183], 0, s[0:1]
	s_waitcnt vmcnt(8)
	v_pk_fma_f32 v[12:13], v[12:13], v[140:141], v[226:227]
	v_pk_fma_f32 v[14:15], v[14:15], v[142:143], v[228:229]
	v_pk_fma_f32 v[8:9], v[8:9], v[136:137], v[230:231]
	v_pk_fma_f32 v[10:11], v[10:11], v[138:139], v[232:233]
	v_cvt_pk_bf16_f32 v12, v12, v13
	v_cvt_pk_bf16_f32 v13, v14, v15
	v_cvt_pk_bf16_f32 v14, v8, v9
	v_cvt_pk_bf16_f32 v15, v10, v11
	global_store_dwordx4 v[182:183], v[12:15], off sc1
	s_waitcnt vmcnt(7)
	v_pk_fma_f32 v[4:5], v[4:5], v[132:133], v[234:235]
	v_pk_fma_f32 v[6:7], v[6:7], v[134:135], v[236:237]
	v_pk_fma_f32 v[0:1], v[0:1], v[128:129], v[238:239]
	v_pk_fma_f32 v[2:3], v[2:3], v[130:131], v[240:241]
	v_cvt_pk_bf16_f32 v4, v4, v5
	v_cvt_pk_bf16_f32 v5, v6, v7
	v_cvt_pk_bf16_f32 v6, v0, v1
	v_cvt_pk_bf16_f32 v7, v2, v3
	global_store_dwordx4 v[182:183], v[4:7], off offset:256 sc1
	s_andn2_b64 vcc, exec, s[4:5]
	s_mov_b64 s[0:1], -1
	s_cbranch_vccnz .LBB0_773
	s_andn2_b64 vcc, exec, s[6:7]
	s_cbranch_vccnz .LBB0_772
	s_barrier
	s_branch .LBB0_772

; __device__ __forceinline__ unsigned cvt_pk_bf16(float lo, float hi) { unsigned r; asm volatile("v_cvt_pk_bf16_f32 %0, %1, %2" : "=v"(r) : "v"(lo), "v"(hi)); return r; }
; __device__ __forceinline__ float bflo(unsigned w) { return __uint_as_float(w << 16); }
; __device__ __forceinline__ float bfhi(unsigned w) { return __uint_as_float(w & 0xffff0000u); }
;     __device__ __forceinline__ void operator()(const f32x4 (&acc)[2][2][4][2], const Unit& u, int wr, int wc, int fr, int fq) const {
;         const int row0 = u.pm * BM + wr * 64 + fr, col0 = u.pn * BM + wc * 32 + 8 * fq;
;         const float* gb = g + (size_t)(u.pm >> 3) * 12288 + col0;
;         f32x4 gv[2][2];
; #pragma unroll
;         for (int bj = 0; bj < 2; ++bj)
; #pragma unroll
;             for (int n = 0; n < 2; ++n) gv[bj][n] = *(const f32x4*)(gb + bj * HALF + n * 4);
; #pragma unroll
;         for (int ai = 0; ai < 2; ++ai)
; #pragma unroll
;             for (int m = 0; m < 4; ++m) { const size_t off = (size_t)(row0 + ai * HALF + m * 16) * 2048 + col0;
; #pragma unroll
;                 for (int bj = 0; bj < 2; ++bj) { f32x4 b0, b1;
;                     if constexpr (sizeof(TB) == 4) { b0 = __builtin_nontemporal_load((const f32x4*)((const float*)base + off + bj * HALF)); b1 = __builtin_nontemporal_load((const f32x4*)((const float*)base + off + bj * HALF + 4)); }
;                     else { const u32x4 t = *(const u32x4*)((const bf16_t*)base + off + bj * HALF);
;                         b0[0] = bflo(t[0]); b0[1] = bfhi(t[0]); b0[2] = bflo(t[1]); b0[3] = bfhi(t[1]); b1[0] = bflo(t[2]); b1[1] = bfhi(t[2]); b1[2] = bflo(t[3]); b1[3] = bfhi(t[3]); }
;                     const f32x4 v0 = b0 + gv[bj][0] * acc[ai][bj][m][0], v1 = b1 + gv[bj][1] * acc[ai][bj][m][1];
;                     u32x4 w; w.x = cvt_pk_bf16(v0[0], v0[1]); w.y = cvt_pk_bf16(v0[2], v0[3]); w.z = cvt_pk_bf16(v1[0], v1[1]); w.w = cvt_pk_bf16(v1[2], v1[3]);
;                     *(u32x4*)(out + off + bj * HALF) = w; } }
.LBB0_1104:
	v_lshl_add_u32 v164, s57, 8, v166
	v_lshl_or_b32 v162, s58, 8, v168
	v_ashrrev_i32_e32 v165, 31, v164
	v_ashrrev_i32_e32 v163, 31, v162
	v_lshlrev_b64 v[120:121], 11, v[164:165]
	v_lshl_add_u64 v[120:121], v[120:121], 0, v[162:163]
	v_lshlrev_b64 v[160:161], 1, v[120:121]
	s_ashr_i32 s0, s57, 3
	s_mul_hi_i32 s1, s0, 0xc000
	s_mul_i32 s0, s0, 0xc000
	s_add_u32 s0, s45, s0
	s_addc_u32 s1, s46, s1
	v_lshl_add_u64 v[124:125], v[162:163], 2, s[0:1]
	v_lshl_add_u64 v[162:163], s[54:55], 0, v[160:161]
	v_lshl_add_u64 v[160:161], s[72:73], 0, v[160:161]
	s_mov_b64 s[0:1], 0x10000
	global_load_dwordx4 v[172:175], v[160:161], off
	global_load_dwordx4 v[176:179], v[160:161], off offset:256
	v_lshl_add_u64 v[160:161], v[160:161], 0, s[0:1]
	global_load_dwordx4 v[132:135], v[124:125], off
	global_load_dwordx4 v[128:131], v[124:125], off offset:16
	global_load_dwordx4 v[120:123], v[124:125], off offset:528
	global_load_dwordx4 v[124:127], v[124:125], off offset:512
	global_load_dwordx4 v[180:183], v[160:161], off
	global_load_dwordx4 v[184:187], v[160:161], off offset:256
	v_lshl_add_u64 v[160:161], v[160:161], 0, s[0:1]
	global_load_dwordx4 v[190:193], v[160:161], off
	global_load_dwordx4 v[194:197], v[160:161], off offset:256
	v_lshl_add_u64 v[160:161], v[160:161], 0, s[0:1]
	global_load_dwordx4 v[198:201], v[160:161], off
	global_load_dwordx4 v[202:205], v[160:161], off offset:256
	s_mov_b64 s[0:1], 0x50000
	v_lshl_add_u64 v[160:161], v[160:161], 0, s[0:1]
	s_mov_b64 s[0:1], 0x10000
	global_load_dwordx4 v[206:209], v[160:161], off
	global_load_dwordx4 v[214:217], v[160:161], off offset:256
	v_lshl_add_u64 v[160:161], v[160:161], 0, s[0:1]
	global_load_dwordx4 v[218:221], v[160:161], off
	global_load_dwordx4 v[222:225], v[160:161], off offset:256
	v_lshl_add_u64 v[160:161], v[160:161], 0, s[0:1]
	global_load_dwordx4 v[226:229], v[160:161], off
	global_load_dwordx4 v[230:233], v[160:161], off offset:256
	v_lshl_add_u64 v[160:161], v[160:161], 0, s[0:1]
	global_load_dwordx4 v[234:237], v[160:161], off
	global_load_dwordx4 v[238:241], v[160:161], off offset:256
	s_waitcnt vmcnt(14)
	s_waitcnt vmcnt(19)
	v_lshlrev_b32_e32 v164, 16, v172
	v_and_b32_e32 v165, 0xffff0000, v172
	v_lshlrev_b32_e32 v172, 16, v173
	v_and_b32_e32 v173, 0xffff0000, v173
	v_lshlrev_b32_e32 v210, 16, v174
	v_and_b32_e32 v211, 0xffff0000, v174
	v_lshlrev_b32_e32 v174, 16, v175
	v_and_b32_e32 v175, 0xffff0000, v175
	v_pk_fma_f32 v[140:141], v[140:141], v[132:133], v[164:165]
	v_pk_fma_f32 v[142:143], v[142:143], v[134:135], v[172:173]
	v_pk_fma_f32 v[136:137], v[136:137], v[128:129], v[210:211]
	v_pk_fma_f32 v[138:139], v[138:139], v[130:131], v[174:175]
	v_cvt_pk_bf16_f32 v140, v140, v141
	v_cvt_pk_bf16_f32 v141, v142, v143
	v_cvt_pk_bf16_f32 v142, v136, v137
	v_cvt_pk_bf16_f32 v143, v138, v139
	global_store_dwordx4 v[162:163], v[140:143], off sc1
	s_waitcnt vmcnt(19)
	v_lshlrev_b32_e32 v164, 16, v176
	v_and_b32_e32 v165, 0xffff0000, v176
	v_lshlrev_b32_e32 v176, 16, v177
	v_and_b32_e32 v177, 0xffff0000, v177
	v_lshlrev_b32_e32 v210, 16, v178
	v_and_b32_e32 v211, 0xffff0000, v178
	v_lshlrev_b32_e32 v178, 16, v179
	v_and_b32_e32 v179, 0xffff0000, v179
	v_pk_fma_f32 v[112:113], v[112:113], v[124:125], v[164:165]
	v_pk_fma_f32 v[114:115], v[114:115], v[126:127], v[176:177]
	v_pk_fma_f32 v[108:109], v[108:109], v[120:121], v[210:211]
	v_pk_fma_f32 v[110:111], v[110:111], v[122:123], v[178:179]
	v_cvt_pk_bf16_f32 v112, v112, v113
	v_cvt_pk_bf16_f32 v113, v114, v115
	v_cvt_pk_bf16_f32 v114, v108, v109
	v_cvt_pk_bf16_f32 v115, v110, v111
	global_store_dwordx4 v[162:163], v[112:115], off offset:256 sc1
	s_mov_b64 s[0:1], 0x10000
	v_lshl_add_u64 v[162:163], v[162:163], 0, s[0:1]
	s_waitcnt vmcnt(15)
	v_lshlrev_b32_e32 v164, 16, v180
	v_and_b32_e32 v165, 0xffff0000, v180
	v_lshlrev_b32_e32 v180, 16, v181
	v_and_b32_e32 v181, 0xffff0000, v181
	v_lshlrev_b32_e32 v210, 16, v182
	v_and_b32_e32 v211, 0xffff0000, v182
	v_lshlrev_b32_e32 v182, 16, v183
	v_and_b32_e32 v183, 0xffff0000, v183
	v_pk_fma_f32 v[116:117], v[116:117], v[132:133], v[164:165]
	v_pk_fma_f32 v[118:119], v[118:119], v[134:135], v[180:181]
	v_pk_fma_f32 v[104:105], v[104:105], v[128:129], v[210:211]
	v_pk_fma_f32 v[106:107], v[106:107], v[130:131], v[182:183]
	v_cvt_pk_bf16_f32 v116, v116, v117
	v_cvt_pk_bf16_f32 v117, v118, v119
	v_cvt_pk_bf16_f32 v118, v104, v105
	v_cvt_pk_bf16_f32 v119, v106, v107
	global_store_dwordx4 v[162:163], v[116:119], off sc1
	s_waitcnt vmcnt(15)
	v_lshlrev_b32_e32 v164, 16, v184
	v_and_b32_e32 v165, 0xffff0000, v184
	v_lshlrev_b32_e32 v184, 16, v185
	v_and_b32_e32 v185, 0xffff0000, v185
	v_lshlrev_b32_e32 v210, 16, v186
	v_and_b32_e32 v211, 0xffff0000, v186
	v_lshlrev_b32_e32 v186, 16, v187
	v_and_b32_e32 v187, 0xffff0000, v187
	v_pk_fma_f32 v[96:97], v[96:97], v[124:125], v[164:165]
	v_pk_fma_f32 v[98:99], v[98:99], v[126:127], v[184:185]
	v_pk_fma_f32 v[92:93], v[92:93], v[120:121], v[210:211]
	v_pk_fma_f32 v[94:95], v[94:95], v[122:123], v[186:187]
	v_cvt_pk_bf16_f32 v96, v96, v97
	v_cvt_pk_bf16_f32 v97, v98, v99
	v_cvt_pk_bf16_f32 v98, v92, v93
	v_cvt_pk_bf16_f32 v99, v94, v95
	global_store_dwordx4 v[162:163], v[96:99], off offset:256 sc1
	s_mov_b64 s[0:1], 0x10000
	v_lshl_add_u64 v[162:163], v[162:163], 0, s[0:1]
	s_waitcnt vmcnt(15)
; __device__ __forceinline__ unsigned cvt_pk_bf16(float lo, float hi) { unsigned r; asm volatile("v_cvt_pk_bf16_f32 %0, %1, %2" : "=v"(r) : "v"(lo), "v"(hi)); return r; }
; __device__ __forceinline__ float bflo(unsigned w) { return __uint_as_float(w << 16); }
; __device__ __forceinline__ float bfhi(unsigned w) { return __uint_as_float(w & 0xffff0000u); }
;     __device__ __forceinline__ void operator()(const f32x4 (&acc)[2][2][4][2], const Unit& u, int wr, int wc, int fr, int fq) const {
;     ...
;             for (int m = 0; m < 4; ++m) { const size_t off = (size_t)(row0 + ai * HALF + m * 16) * 2048 + col0;
; #pragma unroll
;                 for (int bj = 0; bj < 2; ++bj) { f32x4 b0, b1;
;                     if constexpr (sizeof(TB) == 4) { b0 = __builtin_nontemporal_load((const f32x4*)((const float*)base + off + bj * HALF)); b1 = __builtin_nontemporal_load((const f32x4*)((const float*)base + off + bj * HALF + 4)); }
;                     else { const u32x4 t = *(const u32x4*)((const bf16_t*)base + off + bj * HALF);
;                         b0[0] = bflo(t[0]); b0[1] = bfhi(t[0]); b0[2] = bflo(t[1]); b0[3] = bfhi(t[1]); b1[0] = bflo(t[2]); b1[1] = bfhi(t[2]); b1[2] = bflo(t[3]); b1[3] = bfhi(t[3]); }
;                     const f32x4 v0 = b0 + gv[bj][0] * acc[ai][bj][m][0], v1 = b1 + gv[bj][1] * acc[ai][bj][m][1];
;                     u32x4 w; w.x = cvt_pk_bf16(v0[0], v0[1]); w.y = cvt_pk_bf16(v0[2], v0[3]); w.z = cvt_pk_bf16(v1[0], v1[1]); w.w = cvt_pk_bf16(v1[2], v1[3]);
;                     *(u32x4*)(out + off + bj * HALF) = w; } }
	v_lshlrev_b32_e32 v164, 16, v190
	v_and_b32_e32 v165, 0xffff0000, v190
	v_lshlrev_b32_e32 v190, 16, v191
	v_and_b32_e32 v191, 0xffff0000, v191
	v_lshlrev_b32_e32 v210, 16, v192
	v_and_b32_e32 v211, 0xffff0000, v192
	v_lshlrev_b32_e32 v192, 16, v193
	v_and_b32_e32 v193, 0xffff0000, v193
	v_pk_fma_f32 v[100:101], v[100:101], v[132:133], v[164:165]
	v_pk_fma_f32 v[102:103], v[102:103], v[134:135], v[190:191]
	v_pk_fma_f32 v[88:89], v[88:89], v[128:129], v[210:211]
	v_pk_fma_f32 v[90:91], v[90:91], v[130:131], v[192:193]
	v_cvt_pk_bf16_f32 v100, v100, v101
	v_cvt_pk_bf16_f32 v101, v102, v103
	v_cvt_pk_bf16_f32 v102, v88, v89
	v_cvt_pk_bf16_f32 v103, v90, v91
	global_store_dwordx4 v[162:163], v[100:103], off sc1
	s_waitcnt vmcnt(15)
	v_lshlrev_b32_e32 v164, 16, v194
	v_and_b32_e32 v165, 0xffff0000, v194
	v_lshlrev_b32_e32 v194, 16, v195
	v_and_b32_e32 v195, 0xffff0000, v195
	v_lshlrev_b32_e32 v210, 16, v196
	v_and_b32_e32 v211, 0xffff0000, v196
	v_lshlrev_b32_e32 v196, 16, v197
	v_and_b32_e32 v197, 0xffff0000, v197
	v_pk_fma_f32 v[80:81], v[80:81], v[124:125], v[164:165]
	v_pk_fma_f32 v[82:83], v[82:83], v[126:127], v[194:195]
	v_pk_fma_f32 v[76:77], v[76:77], v[120:121], v[210:211]
	v_pk_fma_f32 v[78:79], v[78:79], v[122:123], v[196:197]
	v_cvt_pk_bf16_f32 v80, v80, v81
	v_cvt_pk_bf16_f32 v81, v82, v83
	v_cvt_pk_bf16_f32 v82, v76, v77
	v_cvt_pk_bf16_f32 v83, v78, v79
	global_store_dwordx4 v[162:163], v[80:83], off offset:256 sc1
	s_mov_b64 s[0:1], 0x10000
	v_lshl_add_u64 v[162:163], v[162:163], 0, s[0:1]
	s_waitcnt vmcnt(15)
	v_lshlrev_b32_e32 v164, 16, v198
	v_and_b32_e32 v165, 0xffff0000, v198
	v_lshlrev_b32_e32 v198, 16, v199
	v_and_b32_e32 v199, 0xffff0000, v199
	v_lshlrev_b32_e32 v210, 16, v200
	v_and_b32_e32 v211, 0xffff0000, v200
	v_lshlrev_b32_e32 v200, 16, v201
	v_and_b32_e32 v201, 0xffff0000, v201
	v_pk_fma_f32 v[84:85], v[84:85], v[132:133], v[164:165]
	v_pk_fma_f32 v[86:87], v[86:87], v[134:135], v[198:199]
	v_pk_fma_f32 v[72:73], v[72:73], v[128:129], v[210:211]
	v_pk_fma_f32 v[74:75], v[74:75], v[130:131], v[200:201]
	v_cvt_pk_bf16_f32 v84, v84, v85
	v_cvt_pk_bf16_f32 v85, v86, v87
	v_cvt_pk_bf16_f32 v86, v72, v73
	v_cvt_pk_bf16_f32 v87, v74, v75
	global_store_dwordx4 v[162:163], v[84:87], off sc1
	s_waitcnt vmcnt(15)
	v_lshlrev_b32_e32 v164, 16, v202
	v_and_b32_e32 v165, 0xffff0000, v202
	v_lshlrev_b32_e32 v202, 16, v203
	v_and_b32_e32 v203, 0xffff0000, v203
	v_lshlrev_b32_e32 v210, 16, v204
	v_and_b32_e32 v211, 0xffff0000, v204
	v_lshlrev_b32_e32 v204, 16, v205
	v_and_b32_e32 v205, 0xffff0000, v205
	v_pk_fma_f32 v[68:69], v[68:69], v[124:125], v[164:165]
	v_pk_fma_f32 v[70:71], v[70:71], v[126:127], v[202:203]
	v_pk_fma_f32 v[64:65], v[64:65], v[120:121], v[210:211]
	v_pk_fma_f32 v[66:67], v[66:67], v[122:123], v[204:205]
	v_cvt_pk_bf16_f32 v68, v68, v69
	v_cvt_pk_bf16_f32 v69, v70, v71
	v_cvt_pk_bf16_f32 v70, v64, v65
	v_cvt_pk_bf16_f32 v71, v66, v67
	global_store_dwordx4 v[162:163], v[68:71], off offset:256 sc1
	s_mov_b64 s[0:1], 0x50000
	v_lshl_add_u64 v[162:163], v[162:163], 0, s[0:1]
	s_waitcnt vmcnt(15)
	v_lshlrev_b32_e32 v164, 16, v206
	v_and_b32_e32 v165, 0xffff0000, v206
	v_lshlrev_b32_e32 v206, 16, v207
	v_and_b32_e32 v207, 0xffff0000, v207
	v_lshlrev_b32_e32 v210, 16, v208
	v_and_b32_e32 v211, 0xffff0000, v208
	v_lshlrev_b32_e32 v208, 16, v209
	v_and_b32_e32 v209, 0xffff0000, v209
	v_pk_fma_f32 v[60:61], v[60:61], v[132:133], v[164:165]
	v_pk_fma_f32 v[62:63], v[62:63], v[134:135], v[206:207]
	v_pk_fma_f32 v[56:57], v[56:57], v[128:129], v[210:211]
	v_pk_fma_f32 v[58:59], v[58:59], v[130:131], v[208:209]
	v_cvt_pk_bf16_f32 v60, v60, v61
	v_cvt_pk_bf16_f32 v61, v62, v63
	v_cvt_pk_bf16_f32 v62, v56, v57
	v_cvt_pk_bf16_f32 v63, v58, v59
	global_store_dwordx4 v[162:163], v[60:63], off sc1
	s_waitcnt vmcnt(15)
	v_lshlrev_b32_e32 v164, 16, v214
	v_and_b32_e32 v165, 0xffff0000, v214
	v_lshlrev_b32_e32 v214, 16, v215
	v_and_b32_e32 v215, 0xffff0000, v215
	v_lshlrev_b32_e32 v210, 16, v216
	v_and_b32_e32 v211, 0xffff0000, v216
	v_lshlrev_b32_e32 v216, 16, v217
	v_and_b32_e32 v217, 0xffff0000, v217
	v_pk_fma_f32 v[48:49], v[48:49], v[124:125], v[164:165]
	v_pk_fma_f32 v[50:51], v[50:51], v[126:127], v[214:215]
	v_pk_fma_f32 v[44:45], v[44:45], v[120:121], v[210:211]
	v_pk_fma_f32 v[46:47], v[46:47], v[122:123], v[216:217]
	v_cvt_pk_bf16_f32 v48, v48, v49
	v_cvt_pk_bf16_f32 v49, v50, v51
	v_cvt_pk_bf16_f32 v50, v44, v45
	v_cvt_pk_bf16_f32 v51, v46, v47
	global_store_dwordx4 v[162:163], v[48:51], off offset:256 sc1
	s_mov_b64 s[0:1], 0x10000
	v_lshl_add_u64 v[162:163], v[162:163], 0, s[0:1]
	s_waitcnt vmcnt(15)
; __device__ __forceinline__ unsigned cvt_pk_bf16(float lo, float hi) { unsigned r; asm volatile("v_cvt_pk_bf16_f32 %0, %1, %2" : "=v"(r) : "v"(lo), "v"(hi)); return r; }
; __device__ __forceinline__ float bflo(unsigned w) { return __uint_as_float(w << 16); }
; __device__ __forceinline__ float bfhi(unsigned w) { return __uint_as_float(w & 0xffff0000u); }
;     __device__ __forceinline__ void operator()(const f32x4 (&acc)[2][2][4][2], const Unit& u, int wr, int wc, int fr, int fq) const {
;     ...
;             for (int m = 0; m < 4; ++m) { const size_t off = (size_t)(row0 + ai * HALF + m * 16) * 2048 + col0;
; #pragma unroll
;                 for (int bj = 0; bj < 2; ++bj) { f32x4 b0, b1;
;                     if constexpr (sizeof(TB) == 4) { b0 = __builtin_nontemporal_load((const f32x4*)((const float*)base + off + bj * HALF)); b1 = __builtin_nontemporal_load((const f32x4*)((const float*)base + off + bj * HALF + 4)); }
;                     else { const u32x4 t = *(const u32x4*)((const bf16_t*)base + off + bj * HALF);
;                         b0[0] = bflo(t[0]); b0[1] = bfhi(t[0]); b0[2] = bflo(t[1]); b0[3] = bfhi(t[1]); b1[0] = bflo(t[2]); b1[1] = bfhi(t[2]); b1[2] = bflo(t[3]); b1[3] = bfhi(t[3]); }
;                     const f32x4 v0 = b0 + gv[bj][0] * acc[ai][bj][m][0], v1 = b1 + gv[bj][1] * acc[ai][bj][m][1];
;                     u32x4 w; w.x = cvt_pk_bf16(v0[0], v0[1]); w.y = cvt_pk_bf16(v0[2], v0[3]); w.z = cvt_pk_bf16(v1[0], v1[1]); w.w = cvt_pk_bf16(v1[2], v1[3]);
;                     *(u32x4*)(out + off + bj * HALF) = w; } }
	v_lshlrev_b32_e32 v164, 16, v218
	v_and_b32_e32 v165, 0xffff0000, v218
	v_lshlrev_b32_e32 v218, 16, v219
	v_and_b32_e32 v219, 0xffff0000, v219
	v_lshlrev_b32_e32 v210, 16, v220
	v_and_b32_e32 v211, 0xffff0000, v220
	v_lshlrev_b32_e32 v220, 16, v221
	v_and_b32_e32 v221, 0xffff0000, v221
	v_pk_fma_f32 v[52:53], v[52:53], v[132:133], v[164:165]
	v_pk_fma_f32 v[54:55], v[54:55], v[134:135], v[218:219]
	v_pk_fma_f32 v[40:41], v[40:41], v[128:129], v[210:211]
	v_pk_fma_f32 v[42:43], v[42:43], v[130:131], v[220:221]
	v_cvt_pk_bf16_f32 v52, v52, v53
	v_cvt_pk_bf16_f32 v53, v54, v55
	v_cvt_pk_bf16_f32 v54, v40, v41
	v_cvt_pk_bf16_f32 v55, v42, v43
	global_store_dwordx4 v[162:163], v[52:55], off sc1
	s_waitcnt vmcnt(15)
	v_lshlrev_b32_e32 v164, 16, v222
	v_and_b32_e32 v165, 0xffff0000, v222
	v_lshlrev_b32_e32 v222, 16, v223
	v_and_b32_e32 v223, 0xffff0000, v223
	v_lshlrev_b32_e32 v210, 16, v224
	v_and_b32_e32 v211, 0xffff0000, v224
	v_lshlrev_b32_e32 v224, 16, v225
	v_and_b32_e32 v225, 0xffff0000, v225
	v_pk_fma_f32 v[32:33], v[32:33], v[124:125], v[164:165]
	v_pk_fma_f32 v[34:35], v[34:35], v[126:127], v[222:223]
	v_pk_fma_f32 v[28:29], v[28:29], v[120:121], v[210:211]
	v_pk_fma_f32 v[30:31], v[30:31], v[122:123], v[224:225]
	v_cvt_pk_bf16_f32 v32, v32, v33
	v_cvt_pk_bf16_f32 v33, v34, v35
	v_cvt_pk_bf16_f32 v34, v28, v29
	v_cvt_pk_bf16_f32 v35, v30, v31
	global_store_dwordx4 v[162:163], v[32:35], off offset:256 sc1
	s_mov_b64 s[0:1], 0x10000
	v_lshl_add_u64 v[162:163], v[162:163], 0, s[0:1]
	s_waitcnt vmcnt(15)
	v_lshlrev_b32_e32 v164, 16, v226
	v_and_b32_e32 v165, 0xffff0000, v226
	v_lshlrev_b32_e32 v226, 16, v227
	v_and_b32_e32 v227, 0xffff0000, v227
	v_lshlrev_b32_e32 v210, 16, v228
	v_and_b32_e32 v211, 0xffff0000, v228
	v_lshlrev_b32_e32 v228, 16, v229
	v_and_b32_e32 v229, 0xffff0000, v229
	v_pk_fma_f32 v[36:37], v[36:37], v[132:133], v[164:165]
	v_pk_fma_f32 v[38:39], v[38:39], v[134:135], v[226:227]
	v_pk_fma_f32 v[24:25], v[24:25], v[128:129], v[210:211]
	v_pk_fma_f32 v[26:27], v[26:27], v[130:131], v[228:229]
	v_cvt_pk_bf16_f32 v36, v36, v37
	v_cvt_pk_bf16_f32 v37, v38, v39
	v_cvt_pk_bf16_f32 v38, v24, v25
	v_cvt_pk_bf16_f32 v39, v26, v27
	global_store_dwordx4 v[162:163], v[36:39], off sc1
	s_waitcnt vmcnt(15)
	v_lshlrev_b32_e32 v164, 16, v230
	v_and_b32_e32 v165, 0xffff0000, v230
	v_lshlrev_b32_e32 v230, 16, v231
	v_and_b32_e32 v231, 0xffff0000, v231
	v_lshlrev_b32_e32 v210, 16, v232
	v_and_b32_e32 v211, 0xffff0000, v232
	v_lshlrev_b32_e32 v232, 16, v233
	v_and_b32_e32 v233, 0xffff0000, v233
	v_pk_fma_f32 v[16:17], v[16:17], v[124:125], v[164:165]
	v_pk_fma_f32 v[18:19], v[18:19], v[126:127], v[230:231]
	v_pk_fma_f32 v[12:13], v[12:13], v[120:121], v[210:211]
	v_pk_fma_f32 v[14:15], v[14:15], v[122:123], v[232:233]
	v_cvt_pk_bf16_f32 v16, v16, v17
	v_cvt_pk_bf16_f32 v17, v18, v19
	v_cvt_pk_bf16_f32 v18, v12, v13
	v_cvt_pk_bf16_f32 v19, v14, v15
	global_store_dwordx4 v[162:163], v[16:19], off offset:256 sc1
	s_mov_b64 s[0:1], 0x10000
	v_lshl_add_u64 v[162:163], v[162:163], 0, s[0:1]
	s_waitcnt vmcnt(15)
	v_lshlrev_b32_e32 v164, 16, v234
	v_and_b32_e32 v165, 0xffff0000, v234
	v_lshlrev_b32_e32 v234, 16, v235
	v_and_b32_e32 v235, 0xffff0000, v235
	v_lshlrev_b32_e32 v210, 16, v236
	v_and_b32_e32 v211, 0xffff0000, v236
	v_lshlrev_b32_e32 v236, 16, v237
	v_and_b32_e32 v237, 0xffff0000, v237
	v_pk_fma_f32 v[20:21], v[20:21], v[132:133], v[164:165]
	v_pk_fma_f32 v[22:23], v[22:23], v[134:135], v[234:235]
	v_pk_fma_f32 v[8:9], v[8:9], v[128:129], v[210:211]
	v_pk_fma_f32 v[10:11], v[10:11], v[130:131], v[236:237]
	v_cvt_pk_bf16_f32 v20, v20, v21
	v_cvt_pk_bf16_f32 v21, v22, v23
	v_cvt_pk_bf16_f32 v22, v8, v9
	v_cvt_pk_bf16_f32 v23, v10, v11
	global_store_dwordx4 v[162:163], v[20:23], off sc1
	s_waitcnt vmcnt(15)
	v_lshlrev_b32_e32 v164, 16, v238
	v_and_b32_e32 v165, 0xffff0000, v238
	v_lshlrev_b32_e32 v238, 16, v239
	v_and_b32_e32 v239, 0xffff0000, v239
	v_lshlrev_b32_e32 v210, 16, v240
	v_and_b32_e32 v211, 0xffff0000, v240
	v_lshlrev_b32_e32 v240, 16, v241
	v_and_b32_e32 v241, 0xffff0000, v241
	v_pk_fma_f32 v[4:5], v[4:5], v[124:125], v[164:165]
	v_pk_fma_f32 v[6:7], v[6:7], v[126:127], v[238:239]
	v_pk_fma_f32 v[0:1], v[0:1], v[120:121], v[210:211]
	v_pk_fma_f32 v[2:3], v[2:3], v[122:123], v[240:241]
	v_cvt_pk_bf16_f32 v4, v4, v5
	v_cvt_pk_bf16_f32 v5, v6, v7
	v_cvt_pk_bf16_f32 v6, v0, v1
	v_cvt_pk_bf16_f32 v7, v2, v3
	global_store_dwordx4 v[162:163], v[4:7], off offset:256 sc1
	s_and_b64 vcc, exec, s[2:3]
	s_mov_b64 s[0:1], -1
	s_mov_b32 s22, s48
	s_cbranch_vccnz .LBB0_1089
	s_andn2_b64 vcc, exec, s[6:7]
	s_cbranch_vccnz .LBB0_1088
	s_barrier
	s_branch .LBB0_1088
